# residual epilogues: low-half array (XLO) loads and stores marked nt, high half keeps the default policy
# speedup vs baseline: 1.0043x; 1.0043x over previous
.LBB0_779:
	v_lshl_add_u32 v184, s24, 8, v171
	v_lshl_or_b32 v182, s50, 8, v205
	v_ashrrev_i32_e32 v185, 31, v184
	v_lshlrev_b64 v[128:129], 10, v[184:185]
	v_ashrrev_i32_e32 v183, 31, v182
	v_lshl_add_u64 v[128:129], v[128:129], 0, v[182:183]
	v_readlane_b32 s22, v247, 5
	v_lshlrev_b64 v[128:129], 1, v[128:129]
	v_readlane_b32 s23, v247, 6
	v_readlane_b32 s26, v249, 0
	v_or_b32_e32 v198, 16, v184
	v_lshl_add_u64 v[188:189], s[22:23], 0, v[128:129]
	v_readlane_b32 s27, v249, 1
	global_load_dwordx4 v[194:197], v[188:189], off offset:0
	v_ashrrev_i32_e32 v199, 31, v198
	v_or_b32_e32 v186, 32, v184
	v_lshl_add_u64 v[232:233], s[26:27], 0, v[128:129]
	global_load_dwordx4 v[208:211], v[232:233], off offset:0 nt
	v_lshlrev_b64 v[128:129], 10, v[198:199]
	global_load_dwordx4 v[212:215], v[188:189], off offset:256
	v_lshl_add_u64 v[128:129], v[128:129], 0, v[182:183]
	global_load_dwordx4 v[228:231], v[232:233], off offset:256 nt
	v_lshlrev_b64 v[128:129], 1, v[128:129]
	v_lshl_add_u64 v[200:201], s[22:23], 0, v[128:129]
	global_load_dwordx4 v[152:155], v[200:201], off offset:0
	v_ashrrev_i32_e32 v187, 31, v186
	v_lshl_add_u64 v[202:203], s[26:27], 0, v[128:129]
	global_load_dwordx4 v[156:159], v[202:203], off offset:0 nt
	v_lshlrev_b64 v[128:129], 10, v[186:187]
	global_load_dwordx4 v[148:151], v[200:201], off offset:256
	v_lshl_add_u64 v[128:129], v[128:129], 0, v[182:183]
	global_load_dwordx4 v[144:147], v[202:203], off offset:256 nt
	v_lshlrev_b64 v[128:129], 1, v[128:129]
	v_lshl_add_u64 v[190:191], s[22:23], 0, v[128:129]
	global_load_dwordx4 v[136:139], v[190:191], off offset:0
	v_lshl_add_u64 v[192:193], s[26:27], 0, v[128:129]
	global_load_dwordx4 v[140:143], v[192:193], off offset:0 nt
	global_load_dwordx4 v[132:135], v[190:191], off offset:256
	global_load_dwordx4 v[128:131], v[192:193], off offset:256 nt
	s_waitcnt vmcnt(8)
	s_mov_b32 s4, 0xffff
	v_lshlrev_b32_e32 v207, 16, v195
	v_lshlrev_b32_e32 v234, 16, v194
	v_and_b32_e32 v195, 0xffff0000, v195
	v_and_b32_e32 v194, 0xffff0000, v194
	v_or_b32_sdwa v235, v209, v207 dst_sel:DWORD dst_unused:UNUSED_PAD src0_sel:WORD_0 src1_sel:DWORD
	v_or_b32_sdwa v195, v209, v195 dst_sel:DWORD dst_unused:UNUSED_PAD src0_sel:WORD_1 src1_sel:DWORD
	v_or_b32_sdwa v194, v208, v194 dst_sel:DWORD dst_unused:UNUSED_PAD src0_sel:WORD_1 src1_sel:DWORD
	v_mov_b32_e32 v209, v126
	v_mov_b32_e32 v126, v125
	v_or_b32_sdwa v234, v208, v234 dst_sel:DWORD dst_unused:UNUSED_PAD src0_sel:WORD_0 src1_sel:DWORD
	v_mov_b32_e32 v208, v124
	v_pk_add_f32 v[194:195], v[126:127], v[194:195]
	v_pk_add_f32 v[208:209], v[208:209], v[234:235]
	v_and_b32_e32 v125, 0xffff0000, v194
	v_and_b32_e32 v124, 0xffff0000, v208
	v_mul_f32_e32 v234, v125, v125
	v_fmac_f32_e32 v234, v124, v124
	v_and_b32_e32 v124, 0xffff0000, v209
	v_fmac_f32_e32 v234, v124, v124
	v_and_b32_e32 v126, 0xffff0000, v195
	v_fmac_f32_e32 v234, v126, v126
	v_or_b32_sdwa v124, v208, v125 dst_sel:DWORD dst_unused:UNUSED_PAD src0_sel:WORD_1 src1_sel:DWORD
	v_or_b32_sdwa v125, v209, v126 dst_sel:DWORD dst_unused:UNUSED_PAD src0_sel:WORD_1 src1_sel:DWORD
	v_lshlrev_b32_e32 v126, 16, v197
	v_lshlrev_b32_e32 v207, 16, v196
	v_and_b32_e32 v197, 0xffff0000, v197
	v_and_b32_e32 v196, 0xffff0000, v196
	v_or_b32_sdwa v127, v211, v126 dst_sel:DWORD dst_unused:UNUSED_PAD src0_sel:WORD_0 src1_sel:DWORD
	v_or_b32_sdwa v126, v210, v207 dst_sel:DWORD dst_unused:UNUSED_PAD src0_sel:WORD_0 src1_sel:DWORD
	v_or_b32_sdwa v197, v211, v197 dst_sel:DWORD dst_unused:UNUSED_PAD src0_sel:WORD_1 src1_sel:DWORD
	v_or_b32_sdwa v196, v210, v196 dst_sel:DWORD dst_unused:UNUSED_PAD src0_sel:WORD_1 src1_sel:DWORD
	v_mov_b32_e32 v210, v120
	v_mov_b32_e32 v211, v122
	v_mov_b32_e32 v122, v121
	v_pk_add_f32 v[210:211], v[210:211], v[126:127]
	v_pk_add_f32 v[120:121], v[122:123], v[196:197]
	v_and_b32_e32 v122, 0xffff0000, v210
	v_and_b32_e32 v123, 0xffff0000, v120
	v_and_b32_e32 v197, 0xffff0000, v121
	v_lshlrev_b32_e32 v194, 16, v194
	v_lshlrev_b32_e32 v120, 16, v120
	v_or_b32_sdwa v126, v210, v123 dst_sel:DWORD dst_unused:UNUSED_PAD src0_sel:WORD_1 src1_sel:DWORD
	v_or_b32_sdwa v127, v211, v197 dst_sel:DWORD dst_unused:UNUSED_PAD src0_sel:WORD_1 src1_sel:DWORD
	v_fmac_f32_e32 v234, v122, v122
	v_lshlrev_b32_e32 v195, 16, v195
	v_lshlrev_b32_e32 v121, 16, v121
	v_and_or_b32 v122, v210, s4, v120
	v_and_or_b32 v120, v208, s4, v194
	v_fmac_f32_e32 v234, v123, v123
	v_and_or_b32 v123, v211, s4, v121
	v_and_or_b32 v121, v209, s4, v195
	global_store_dwordx4 v[188:189], v[124:127], off
	global_store_dwordx4 v[232:233], v[120:123], off nt
	v_and_b32_e32 v196, 0xffff0000, v211
	v_and_b32_e32 v124, 0xffff0000, v212
	v_lshlrev_b32_e32 v120, 16, v213
	v_lshlrev_b32_e32 v122, 16, v212
	v_or_b32_sdwa v121, v229, v120 dst_sel:DWORD dst_unused:UNUSED_PAD src0_sel:WORD_0 src1_sel:DWORD
	v_or_b32_sdwa v120, v228, v122 dst_sel:DWORD dst_unused:UNUSED_PAD src0_sel:WORD_0 src1_sel:DWORD
	v_and_b32_e32 v122, 0xffff0000, v213
	v_or_b32_sdwa v123, v229, v122 dst_sel:DWORD dst_unused:UNUSED_PAD src0_sel:WORD_1 src1_sel:DWORD
	v_or_b32_sdwa v122, v228, v124 dst_sel:DWORD dst_unused:UNUSED_PAD src0_sel:WORD_1 src1_sel:DWORD
	v_mov_b32_e32 v124, v116
	v_mov_b32_e32 v125, v118
	v_fmac_f32_e32 v234, v196, v196
	v_pk_add_f32 v[120:121], v[124:125], v[120:121]
	v_mov_b32_e32 v118, v117
	v_fmac_f32_e32 v234, v197, v197
	v_pk_add_f32 v[122:123], v[118:119], v[122:123]
	v_and_b32_e32 v116, 0xffff0000, v120
	v_lshlrev_b32_e32 v118, 16, v215
	v_lshlrev_b32_e32 v124, 16, v214
	v_fmac_f32_e32 v234, v116, v116
	v_and_b32_e32 v116, 0xffff0000, v122
	v_or_b32_sdwa v119, v231, v118 dst_sel:DWORD dst_unused:UNUSED_PAD src0_sel:WORD_0 src1_sel:DWORD
	v_or_b32_sdwa v118, v230, v124 dst_sel:DWORD dst_unused:UNUSED_PAD src0_sel:WORD_0 src1_sel:DWORD
	v_and_b32_e32 v124, 0xffff0000, v215
	v_and_b32_e32 v126, 0xffff0000, v214
	v_fmac_f32_e32 v234, v116, v116
	v_and_b32_e32 v117, 0xffff0000, v121
	v_or_b32_sdwa v125, v231, v124 dst_sel:DWORD dst_unused:UNUSED_PAD src0_sel:WORD_1 src1_sel:DWORD
	v_or_b32_sdwa v124, v230, v126 dst_sel:DWORD dst_unused:UNUSED_PAD src0_sel:WORD_1 src1_sel:DWORD
	v_mov_b32_e32 v126, v112
	v_mov_b32_e32 v127, v114
	v_fmac_f32_e32 v234, v117, v117
	v_and_b32_e32 v117, 0xffff0000, v123
	v_pk_add_f32 v[126:127], v[126:127], v[118:119]
	v_mov_b32_e32 v114, v113
	v_fmac_f32_e32 v234, v117, v117
	v_pk_add_f32 v[112:113], v[114:115], v[124:125]
	v_and_b32_e32 v114, 0xffff0000, v126
	v_and_b32_e32 v115, 0xffff0000, v112
	v_fmac_f32_e32 v234, v114, v114
	v_and_b32_e32 v124, 0xffff0000, v127
	v_or_b32_sdwa v118, v126, v115 dst_sel:DWORD dst_unused:UNUSED_PAD src0_sel:WORD_1 src1_sel:DWORD
	v_fmac_f32_e32 v234, v115, v115
	v_lshlrev_b32_e32 v115, 16, v123
	v_and_b32_e32 v123, 64, v221
	v_fmac_f32_e32 v234, v124, v124
	v_lshlrev_b32_e32 v114, 16, v122
	v_xor_b32_e32 v122, 16, v221
	v_add_u32_e32 v124, 64, v123
	v_cmp_lt_i32_e32 vcc, v122, v124
	v_and_b32_e32 v125, 0xffff0000, v113
	v_fmac_f32_e32 v234, v125, v125
	v_cndmask_b32_e32 v122, v221, v122, vcc
	v_lshlrev_b32_e32 v207, 2, v122
	v_or_b32_sdwa v119, v127, v125 dst_sel:DWORD dst_unused:UNUSED_PAD src0_sel:WORD_1 src1_sel:DWORD
	ds_bpermute_b32 v125, v207, v234
	v_lshlrev_b32_e32 v113, 16, v113
	v_and_or_b32 v123, v127, s4, v113
	v_xor_b32_e32 v113, 32, v221
	v_cmp_lt_i32_e32 vcc, v113, v124
	v_lshlrev_b32_e32 v112, 16, v112
	v_and_or_b32 v122, v126, s4, v112
	v_cndmask_b32_e32 v113, v221, v113, vcc
	s_waitcnt lgkmcnt(0)
	v_add_f32_e32 v112, v234, v125
	v_lshlrev_b32_e32 v208, 2, v113
	ds_bpermute_b32 v113, v208, v112
	v_or_b32_sdwa v116, v120, v116 dst_sel:DWORD dst_unused:UNUSED_PAD src0_sel:WORD_1 src1_sel:DWORD
	v_or_b32_sdwa v117, v121, v117 dst_sel:DWORD dst_unused:UNUSED_PAD src0_sel:WORD_1 src1_sel:DWORD
	v_and_or_b32 v121, v121, s4, v115
	v_and_or_b32 v120, v120, s4, v114
	global_store_dwordx4 v[188:189], v[116:119], off offset:256
	global_store_dwordx4 v[232:233], v[120:123], off offset:256 nt
	s_and_saveexec_b64 s[22:23], s[6:7]
	s_cbranch_execz .LBB0_781
	v_lshlrev_b64 v[114:115], 6, v[184:185]
	s_lshl_b32 s26, s50, 2
	v_lshl_add_u64 v[114:115], s[2:3], 0, v[114:115]
	s_ashr_i32 s27, s26, 31
	v_lshl_add_u64 v[114:115], s[26:27], 2, v[114:115]
	s_lshl_b32 s24, s46, 2
	v_lshl_add_u64 v[114:115], v[114:115], 0, s[24:25]
	s_waitcnt lgkmcnt(0)
	v_add_f32_e32 v112, v112, v113
	global_store_dword v[114:115], v112, off
.LBB0_781:
	s_or_b64 exec, exec, s[22:23]
	v_or_b32_e32 v188, 48, v184
	v_ashrrev_i32_e32 v189, 31, v188
	s_waitcnt lgkmcnt(0)
	v_lshlrev_b64 v[112:113], 10, v[188:189]
	v_lshl_add_u64 v[112:113], v[112:113], 0, v[182:183]
	v_readlane_b32 s22, v247, 5
	v_lshlrev_b64 v[112:113], 1, v[112:113]
	v_readlane_b32 s23, v247, 6
	s_nop 1
	v_lshl_add_u64 v[194:195], s[22:23], 0, v[112:113]
	v_readlane_b32 s22, v249, 0
	v_readlane_b32 s23, v249, 1
	global_load_dwordx4 v[120:123], v[194:195], off offset:0
	s_nop 1
	v_lshl_add_u64 v[196:197], s[22:23], 0, v[112:113]
	global_load_dwordx4 v[124:127], v[196:197], off offset:0 nt
	global_load_dwordx4 v[116:119], v[194:195], off offset:256
	global_load_dwordx4 v[112:115], v[196:197], off offset:256 nt
	s_waitcnt vmcnt(8)
	s_nop 0
	v_lshlrev_b32_e32 v185, 16, v153
	v_lshlrev_b32_e32 v209, 16, v152
	v_and_b32_e32 v153, 0xffff0000, v153
	v_and_b32_e32 v152, 0xffff0000, v152
	v_or_b32_sdwa v211, v157, v185 dst_sel:DWORD dst_unused:UNUSED_PAD src0_sel:WORD_0 src1_sel:DWORD
	v_or_b32_sdwa v153, v157, v153 dst_sel:DWORD dst_unused:UNUSED_PAD src0_sel:WORD_1 src1_sel:DWORD
	v_or_b32_sdwa v152, v156, v152 dst_sel:DWORD dst_unused:UNUSED_PAD src0_sel:WORD_1 src1_sel:DWORD
	v_mov_b32_e32 v157, v110
	v_mov_b32_e32 v110, v109
	v_or_b32_sdwa v210, v156, v209 dst_sel:DWORD dst_unused:UNUSED_PAD src0_sel:WORD_0 src1_sel:DWORD
	v_mov_b32_e32 v156, v108
	v_pk_add_f32 v[152:153], v[110:111], v[152:153]
	v_pk_add_f32 v[156:157], v[156:157], v[210:211]
	v_and_b32_e32 v109, 0xffff0000, v152
	v_and_b32_e32 v108, 0xffff0000, v156
	v_mul_f32_e32 v185, v109, v109
	v_fmac_f32_e32 v185, v108, v108
	v_and_b32_e32 v108, 0xffff0000, v157
	v_fmac_f32_e32 v185, v108, v108
	v_and_b32_e32 v110, 0xffff0000, v153
	v_fmac_f32_e32 v185, v110, v110
	v_or_b32_sdwa v108, v156, v109 dst_sel:DWORD dst_unused:UNUSED_PAD src0_sel:WORD_1 src1_sel:DWORD
	v_or_b32_sdwa v109, v157, v110 dst_sel:DWORD dst_unused:UNUSED_PAD src0_sel:WORD_1 src1_sel:DWORD
	v_lshlrev_b32_e32 v110, 16, v155
	v_lshlrev_b32_e32 v209, 16, v154
	v_and_b32_e32 v155, 0xffff0000, v155
	v_and_b32_e32 v154, 0xffff0000, v154
	v_or_b32_sdwa v111, v159, v110 dst_sel:DWORD dst_unused:UNUSED_PAD src0_sel:WORD_0 src1_sel:DWORD
	v_or_b32_sdwa v110, v158, v209 dst_sel:DWORD dst_unused:UNUSED_PAD src0_sel:WORD_0 src1_sel:DWORD
	v_or_b32_sdwa v155, v159, v155 dst_sel:DWORD dst_unused:UNUSED_PAD src0_sel:WORD_1 src1_sel:DWORD
	v_or_b32_sdwa v154, v158, v154 dst_sel:DWORD dst_unused:UNUSED_PAD src0_sel:WORD_1 src1_sel:DWORD
	v_mov_b32_e32 v158, v104
	v_mov_b32_e32 v159, v106
	v_mov_b32_e32 v106, v105
	v_pk_add_f32 v[158:159], v[158:159], v[110:111]
	v_pk_add_f32 v[104:105], v[106:107], v[154:155]
	v_and_b32_e32 v106, 0xffff0000, v158
	v_and_b32_e32 v107, 0xffff0000, v104
	v_and_b32_e32 v155, 0xffff0000, v105
	v_lshlrev_b32_e32 v152, 16, v152
	v_lshlrev_b32_e32 v104, 16, v104
	v_or_b32_sdwa v110, v158, v107 dst_sel:DWORD dst_unused:UNUSED_PAD src0_sel:WORD_1 src1_sel:DWORD
	v_or_b32_sdwa v111, v159, v155 dst_sel:DWORD dst_unused:UNUSED_PAD src0_sel:WORD_1 src1_sel:DWORD
	v_fmac_f32_e32 v185, v106, v106
	v_lshlrev_b32_e32 v153, 16, v153
	v_lshlrev_b32_e32 v105, 16, v105
	v_and_or_b32 v106, v158, s4, v104
	v_and_or_b32 v104, v156, s4, v152
	v_fmac_f32_e32 v185, v107, v107
	v_and_or_b32 v107, v159, s4, v105
	v_and_or_b32 v105, v157, s4, v153
	global_store_dwordx4 v[200:201], v[108:111], off
	global_store_dwordx4 v[202:203], v[104:107], off nt
	v_and_b32_e32 v154, 0xffff0000, v159
	v_and_b32_e32 v108, 0xffff0000, v148
	v_lshlrev_b32_e32 v104, 16, v149
	v_lshlrev_b32_e32 v106, 16, v148
	v_or_b32_sdwa v105, v145, v104 dst_sel:DWORD dst_unused:UNUSED_PAD src0_sel:WORD_0 src1_sel:DWORD
	v_or_b32_sdwa v104, v144, v106 dst_sel:DWORD dst_unused:UNUSED_PAD src0_sel:WORD_0 src1_sel:DWORD
	v_and_b32_e32 v106, 0xffff0000, v149
	v_or_b32_sdwa v107, v145, v106 dst_sel:DWORD dst_unused:UNUSED_PAD src0_sel:WORD_1 src1_sel:DWORD
	v_or_b32_sdwa v106, v144, v108 dst_sel:DWORD dst_unused:UNUSED_PAD src0_sel:WORD_1 src1_sel:DWORD
	v_mov_b32_e32 v108, v100
	v_mov_b32_e32 v109, v102
	v_fmac_f32_e32 v185, v154, v154
	v_pk_add_f32 v[104:105], v[108:109], v[104:105]
	v_mov_b32_e32 v102, v101
	v_fmac_f32_e32 v185, v155, v155
	v_pk_add_f32 v[106:107], v[102:103], v[106:107]
	v_and_b32_e32 v100, 0xffff0000, v104
	v_lshlrev_b32_e32 v102, 16, v151
	v_lshlrev_b32_e32 v108, 16, v150
	v_fmac_f32_e32 v185, v100, v100
	v_and_b32_e32 v100, 0xffff0000, v106
	v_or_b32_sdwa v103, v147, v102 dst_sel:DWORD dst_unused:UNUSED_PAD src0_sel:WORD_0 src1_sel:DWORD
	v_or_b32_sdwa v102, v146, v108 dst_sel:DWORD dst_unused:UNUSED_PAD src0_sel:WORD_0 src1_sel:DWORD
	v_and_b32_e32 v108, 0xffff0000, v151
	v_and_b32_e32 v110, 0xffff0000, v150
	v_fmac_f32_e32 v185, v100, v100
	v_and_b32_e32 v101, 0xffff0000, v105
	v_or_b32_sdwa v109, v147, v108 dst_sel:DWORD dst_unused:UNUSED_PAD src0_sel:WORD_1 src1_sel:DWORD
	v_or_b32_sdwa v108, v146, v110 dst_sel:DWORD dst_unused:UNUSED_PAD src0_sel:WORD_1 src1_sel:DWORD
	v_mov_b32_e32 v110, v96
	v_mov_b32_e32 v111, v98
	v_fmac_f32_e32 v185, v101, v101
	v_and_b32_e32 v101, 0xffff0000, v107
	v_pk_add_f32 v[110:111], v[110:111], v[102:103]
	v_mov_b32_e32 v98, v97
	v_fmac_f32_e32 v185, v101, v101
	v_pk_add_f32 v[96:97], v[98:99], v[108:109]
	v_and_b32_e32 v98, 0xffff0000, v110
	v_and_b32_e32 v99, 0xffff0000, v96
	v_fmac_f32_e32 v185, v98, v98
	v_and_b32_e32 v108, 0xffff0000, v111
	v_fmac_f32_e32 v185, v99, v99
	v_and_b32_e32 v109, 0xffff0000, v97
	v_fmac_f32_e32 v185, v108, v108
	v_fmac_f32_e32 v185, v109, v109
	ds_bpermute_b32 v108, v207, v185
	v_lshlrev_b32_e32 v96, 16, v96
	v_lshlrev_b32_e32 v98, 16, v106
	v_lshlrev_b32_e32 v97, 16, v97
	v_and_or_b32 v106, v110, s4, v96
	s_waitcnt lgkmcnt(0)
	v_add_f32_e32 v96, v185, v108
	v_or_b32_sdwa v102, v110, v99 dst_sel:DWORD dst_unused:UNUSED_PAD src0_sel:WORD_1 src1_sel:DWORD
	v_lshlrev_b32_e32 v99, 16, v107
	v_and_or_b32 v107, v111, s4, v97
	ds_bpermute_b32 v97, v208, v96
	v_or_b32_sdwa v100, v104, v100 dst_sel:DWORD dst_unused:UNUSED_PAD src0_sel:WORD_1 src1_sel:DWORD
	v_or_b32_sdwa v101, v105, v101 dst_sel:DWORD dst_unused:UNUSED_PAD src0_sel:WORD_1 src1_sel:DWORD
	v_or_b32_sdwa v103, v111, v109 dst_sel:DWORD dst_unused:UNUSED_PAD src0_sel:WORD_1 src1_sel:DWORD
	v_and_or_b32 v105, v105, s4, v99
	v_and_or_b32 v104, v104, s4, v98
	global_store_dwordx4 v[200:201], v[100:103], off offset:256
	global_store_dwordx4 v[202:203], v[104:107], off offset:256 nt
	s_and_saveexec_b64 s[22:23], s[6:7]
	s_cbranch_execz .LBB0_783
	v_lshlrev_b64 v[98:99], 6, v[198:199]
	s_lshl_b32 s26, s50, 2
	v_lshl_add_u64 v[98:99], s[2:3], 0, v[98:99]
	s_ashr_i32 s27, s26, 31
	v_lshl_add_u64 v[98:99], s[26:27], 2, v[98:99]
	s_lshl_b32 s24, s46, 2
	v_lshl_add_u64 v[98:99], v[98:99], 0, s[24:25]
	s_waitcnt lgkmcnt(0)
	v_add_f32_e32 v96, v96, v97
	global_store_dword v[98:99], v96, off
.LBB0_783:
	s_or_b64 exec, exec, s[22:23]
	v_add_u32_e32 v144, 0x80, v184
	v_ashrrev_i32_e32 v145, 31, v144
	s_waitcnt lgkmcnt(0)
	v_lshlrev_b64 v[96:97], 10, v[144:145]
	v_lshl_add_u64 v[96:97], v[96:97], 0, v[182:183]
	v_readlane_b32 s22, v247, 5
	v_lshlrev_b64 v[96:97], 1, v[96:97]
	v_readlane_b32 s23, v247, 6
	s_nop 1
	v_lshl_add_u64 v[146:147], s[22:23], 0, v[96:97]
	v_readlane_b32 s22, v249, 0
	v_readlane_b32 s23, v249, 1
	global_load_dwordx4 v[104:107], v[146:147], off offset:0
	s_nop 1
	v_lshl_add_u64 v[148:149], s[22:23], 0, v[96:97]
	global_load_dwordx4 v[108:111], v[148:149], off offset:0 nt
	global_load_dwordx4 v[100:103], v[146:147], off offset:256
	global_load_dwordx4 v[96:99], v[148:149], off offset:256 nt
	s_waitcnt vmcnt(8)
	s_nop 0
	v_lshlrev_b32_e32 v150, 16, v137
	v_lshlrev_b32_e32 v152, 16, v136
	v_and_b32_e32 v137, 0xffff0000, v137
	v_and_b32_e32 v136, 0xffff0000, v136
	v_or_b32_sdwa v151, v141, v150 dst_sel:DWORD dst_unused:UNUSED_PAD src0_sel:WORD_0 src1_sel:DWORD
	v_or_b32_sdwa v137, v141, v137 dst_sel:DWORD dst_unused:UNUSED_PAD src0_sel:WORD_1 src1_sel:DWORD
	v_or_b32_sdwa v136, v140, v136 dst_sel:DWORD dst_unused:UNUSED_PAD src0_sel:WORD_1 src1_sel:DWORD
	v_mov_b32_e32 v141, v94
	v_mov_b32_e32 v94, v93
	v_or_b32_sdwa v150, v140, v152 dst_sel:DWORD dst_unused:UNUSED_PAD src0_sel:WORD_0 src1_sel:DWORD
	v_mov_b32_e32 v140, v92
	v_pk_add_f32 v[136:137], v[94:95], v[136:137]
	v_pk_add_f32 v[140:141], v[140:141], v[150:151]
	v_and_b32_e32 v93, 0xffff0000, v136
	v_and_b32_e32 v92, 0xffff0000, v140
	v_mul_f32_e32 v150, v93, v93
	v_fmac_f32_e32 v150, v92, v92
	v_and_b32_e32 v92, 0xffff0000, v141
	v_fmac_f32_e32 v150, v92, v92
	v_and_b32_e32 v94, 0xffff0000, v137
	v_fmac_f32_e32 v150, v94, v94
	v_or_b32_sdwa v92, v140, v93 dst_sel:DWORD dst_unused:UNUSED_PAD src0_sel:WORD_1 src1_sel:DWORD
	v_or_b32_sdwa v93, v141, v94 dst_sel:DWORD dst_unused:UNUSED_PAD src0_sel:WORD_1 src1_sel:DWORD
	v_lshlrev_b32_e32 v94, 16, v139
	v_lshlrev_b32_e32 v151, 16, v138
	v_and_b32_e32 v139, 0xffff0000, v139
	v_and_b32_e32 v138, 0xffff0000, v138
	v_or_b32_sdwa v95, v143, v94 dst_sel:DWORD dst_unused:UNUSED_PAD src0_sel:WORD_0 src1_sel:DWORD
	v_or_b32_sdwa v94, v142, v151 dst_sel:DWORD dst_unused:UNUSED_PAD src0_sel:WORD_0 src1_sel:DWORD
	v_or_b32_sdwa v139, v143, v139 dst_sel:DWORD dst_unused:UNUSED_PAD src0_sel:WORD_1 src1_sel:DWORD
	v_or_b32_sdwa v138, v142, v138 dst_sel:DWORD dst_unused:UNUSED_PAD src0_sel:WORD_1 src1_sel:DWORD
	v_mov_b32_e32 v142, v88
	v_mov_b32_e32 v143, v90
	v_mov_b32_e32 v90, v89
	v_pk_add_f32 v[142:143], v[142:143], v[94:95]
	v_pk_add_f32 v[88:89], v[90:91], v[138:139]
	v_and_b32_e32 v90, 0xffff0000, v142
	v_and_b32_e32 v91, 0xffff0000, v88
	v_and_b32_e32 v139, 0xffff0000, v89
	v_lshlrev_b32_e32 v136, 16, v136
	v_lshlrev_b32_e32 v88, 16, v88
	v_or_b32_sdwa v94, v142, v91 dst_sel:DWORD dst_unused:UNUSED_PAD src0_sel:WORD_1 src1_sel:DWORD
	v_or_b32_sdwa v95, v143, v139 dst_sel:DWORD dst_unused:UNUSED_PAD src0_sel:WORD_1 src1_sel:DWORD
	v_fmac_f32_e32 v150, v90, v90
	v_lshlrev_b32_e32 v137, 16, v137
	v_lshlrev_b32_e32 v89, 16, v89
	v_and_or_b32 v90, v142, s4, v88
	v_and_or_b32 v88, v140, s4, v136
	v_fmac_f32_e32 v150, v91, v91
	v_and_or_b32 v91, v143, s4, v89
	v_and_or_b32 v89, v141, s4, v137
	global_store_dwordx4 v[190:191], v[92:95], off
	global_store_dwordx4 v[192:193], v[88:91], off nt
	v_and_b32_e32 v138, 0xffff0000, v143
	v_and_b32_e32 v92, 0xffff0000, v132
	v_lshlrev_b32_e32 v88, 16, v133
	v_lshlrev_b32_e32 v90, 16, v132
	v_or_b32_sdwa v89, v129, v88 dst_sel:DWORD dst_unused:UNUSED_PAD src0_sel:WORD_0 src1_sel:DWORD
	v_or_b32_sdwa v88, v128, v90 dst_sel:DWORD dst_unused:UNUSED_PAD src0_sel:WORD_0 src1_sel:DWORD
	v_and_b32_e32 v90, 0xffff0000, v133
	v_or_b32_sdwa v91, v129, v90 dst_sel:DWORD dst_unused:UNUSED_PAD src0_sel:WORD_1 src1_sel:DWORD
	v_or_b32_sdwa v90, v128, v92 dst_sel:DWORD dst_unused:UNUSED_PAD src0_sel:WORD_1 src1_sel:DWORD
	v_mov_b32_e32 v92, v84
	v_mov_b32_e32 v93, v86
	v_fmac_f32_e32 v150, v138, v138
	v_pk_add_f32 v[88:89], v[92:93], v[88:89]
	v_mov_b32_e32 v86, v85
	v_fmac_f32_e32 v150, v139, v139
	v_pk_add_f32 v[90:91], v[86:87], v[90:91]
	v_and_b32_e32 v84, 0xffff0000, v88
	v_lshlrev_b32_e32 v86, 16, v135
	v_lshlrev_b32_e32 v92, 16, v134
	v_fmac_f32_e32 v150, v84, v84
	v_and_b32_e32 v84, 0xffff0000, v90
	v_or_b32_sdwa v87, v131, v86 dst_sel:DWORD dst_unused:UNUSED_PAD src0_sel:WORD_0 src1_sel:DWORD
	v_or_b32_sdwa v86, v130, v92 dst_sel:DWORD dst_unused:UNUSED_PAD src0_sel:WORD_0 src1_sel:DWORD
	v_and_b32_e32 v92, 0xffff0000, v135
	v_and_b32_e32 v94, 0xffff0000, v134
	v_fmac_f32_e32 v150, v84, v84
	v_and_b32_e32 v85, 0xffff0000, v89
	v_or_b32_sdwa v93, v131, v92 dst_sel:DWORD dst_unused:UNUSED_PAD src0_sel:WORD_1 src1_sel:DWORD
	v_or_b32_sdwa v92, v130, v94 dst_sel:DWORD dst_unused:UNUSED_PAD src0_sel:WORD_1 src1_sel:DWORD
	v_mov_b32_e32 v94, v80
	v_mov_b32_e32 v95, v82
	v_fmac_f32_e32 v150, v85, v85
	v_and_b32_e32 v85, 0xffff0000, v91
	v_pk_add_f32 v[94:95], v[94:95], v[86:87]
	v_mov_b32_e32 v82, v81
	v_fmac_f32_e32 v150, v85, v85
	v_pk_add_f32 v[80:81], v[82:83], v[92:93]
	v_and_b32_e32 v82, 0xffff0000, v94
	v_and_b32_e32 v83, 0xffff0000, v80
	v_fmac_f32_e32 v150, v82, v82
	v_and_b32_e32 v92, 0xffff0000, v95
	v_fmac_f32_e32 v150, v83, v83
	v_and_b32_e32 v93, 0xffff0000, v81
	v_fmac_f32_e32 v150, v92, v92
	v_fmac_f32_e32 v150, v93, v93
	ds_bpermute_b32 v92, v207, v150
	v_lshlrev_b32_e32 v80, 16, v80
	v_lshlrev_b32_e32 v82, 16, v90
	v_lshlrev_b32_e32 v81, 16, v81
	v_and_or_b32 v90, v94, s4, v80
	s_waitcnt lgkmcnt(0)
	v_add_f32_e32 v80, v150, v92
	v_or_b32_sdwa v86, v94, v83 dst_sel:DWORD dst_unused:UNUSED_PAD src0_sel:WORD_1 src1_sel:DWORD
	v_lshlrev_b32_e32 v83, 16, v91
	v_and_or_b32 v91, v95, s4, v81
	ds_bpermute_b32 v81, v208, v80
	v_or_b32_sdwa v84, v88, v84 dst_sel:DWORD dst_unused:UNUSED_PAD src0_sel:WORD_1 src1_sel:DWORD
	v_or_b32_sdwa v85, v89, v85 dst_sel:DWORD dst_unused:UNUSED_PAD src0_sel:WORD_1 src1_sel:DWORD
	v_or_b32_sdwa v87, v95, v93 dst_sel:DWORD dst_unused:UNUSED_PAD src0_sel:WORD_1 src1_sel:DWORD
	v_and_or_b32 v89, v89, s4, v83
	v_and_or_b32 v88, v88, s4, v82
	global_store_dwordx4 v[190:191], v[84:87], off offset:256
	global_store_dwordx4 v[192:193], v[88:91], off offset:256 nt
	s_and_saveexec_b64 s[22:23], s[6:7]
	s_cbranch_execz .LBB0_785
	v_lshlrev_b64 v[82:83], 6, v[186:187]
	s_lshl_b32 s26, s50, 2
	v_lshl_add_u64 v[82:83], s[2:3], 0, v[82:83]
	s_ashr_i32 s27, s26, 31
	v_lshl_add_u64 v[82:83], s[26:27], 2, v[82:83]
	s_lshl_b32 s24, s46, 2
	v_lshl_add_u64 v[82:83], v[82:83], 0, s[24:25]
	s_waitcnt lgkmcnt(0)
	v_add_f32_e32 v80, v80, v81
	global_store_dword v[82:83], v80, off
.LBB0_785:
	s_or_b64 exec, exec, s[22:23]
	v_add_u32_e32 v128, 0x90, v184
	v_ashrrev_i32_e32 v129, 31, v128
	s_waitcnt lgkmcnt(0)
	v_lshlrev_b64 v[80:81], 10, v[128:129]
	v_lshl_add_u64 v[80:81], v[80:81], 0, v[182:183]
	v_readlane_b32 s22, v247, 5
	v_lshlrev_b64 v[80:81], 1, v[80:81]
	v_readlane_b32 s23, v247, 6
	s_nop 1
	v_lshl_add_u64 v[130:131], s[22:23], 0, v[80:81]
	v_readlane_b32 s22, v249, 0
	v_readlane_b32 s23, v249, 1
	global_load_dwordx4 v[88:91], v[130:131], off offset:0
	s_nop 1
	v_lshl_add_u64 v[132:133], s[22:23], 0, v[80:81]
	global_load_dwordx4 v[92:95], v[132:133], off offset:0 nt
	global_load_dwordx4 v[84:87], v[130:131], off offset:256
	global_load_dwordx4 v[80:83], v[132:133], off offset:256 nt
	s_waitcnt vmcnt(8)
	s_nop 0
	v_lshlrev_b32_e32 v134, 16, v121
	v_lshlrev_b32_e32 v136, 16, v120
	v_and_b32_e32 v121, 0xffff0000, v121
	v_and_b32_e32 v120, 0xffff0000, v120
	v_or_b32_sdwa v135, v125, v134 dst_sel:DWORD dst_unused:UNUSED_PAD src0_sel:WORD_0 src1_sel:DWORD
	v_or_b32_sdwa v121, v125, v121 dst_sel:DWORD dst_unused:UNUSED_PAD src0_sel:WORD_1 src1_sel:DWORD
	v_or_b32_sdwa v120, v124, v120 dst_sel:DWORD dst_unused:UNUSED_PAD src0_sel:WORD_1 src1_sel:DWORD
	v_mov_b32_e32 v125, v78
	v_mov_b32_e32 v78, v77
	v_or_b32_sdwa v134, v124, v136 dst_sel:DWORD dst_unused:UNUSED_PAD src0_sel:WORD_0 src1_sel:DWORD
	v_mov_b32_e32 v124, v76
	v_pk_add_f32 v[120:121], v[78:79], v[120:121]
	v_pk_add_f32 v[124:125], v[124:125], v[134:135]
	v_and_b32_e32 v77, 0xffff0000, v120
	v_and_b32_e32 v76, 0xffff0000, v124
	v_mul_f32_e32 v134, v77, v77
	v_fmac_f32_e32 v134, v76, v76
	v_and_b32_e32 v76, 0xffff0000, v125
	v_fmac_f32_e32 v134, v76, v76
	v_and_b32_e32 v78, 0xffff0000, v121
	v_fmac_f32_e32 v134, v78, v78
	v_or_b32_sdwa v76, v124, v77 dst_sel:DWORD dst_unused:UNUSED_PAD src0_sel:WORD_1 src1_sel:DWORD
	v_or_b32_sdwa v77, v125, v78 dst_sel:DWORD dst_unused:UNUSED_PAD src0_sel:WORD_1 src1_sel:DWORD
	v_lshlrev_b32_e32 v78, 16, v123
	v_lshlrev_b32_e32 v135, 16, v122
	v_and_b32_e32 v123, 0xffff0000, v123
	v_and_b32_e32 v122, 0xffff0000, v122
	v_or_b32_sdwa v79, v127, v78 dst_sel:DWORD dst_unused:UNUSED_PAD src0_sel:WORD_0 src1_sel:DWORD
	v_or_b32_sdwa v78, v126, v135 dst_sel:DWORD dst_unused:UNUSED_PAD src0_sel:WORD_0 src1_sel:DWORD
	v_or_b32_sdwa v123, v127, v123 dst_sel:DWORD dst_unused:UNUSED_PAD src0_sel:WORD_1 src1_sel:DWORD
	v_or_b32_sdwa v122, v126, v122 dst_sel:DWORD dst_unused:UNUSED_PAD src0_sel:WORD_1 src1_sel:DWORD
	v_mov_b32_e32 v126, v72
	v_mov_b32_e32 v127, v74
	v_mov_b32_e32 v74, v73
	v_pk_add_f32 v[126:127], v[126:127], v[78:79]
	v_pk_add_f32 v[72:73], v[74:75], v[122:123]
	v_and_b32_e32 v74, 0xffff0000, v126
	v_and_b32_e32 v75, 0xffff0000, v72
	v_and_b32_e32 v123, 0xffff0000, v73
	v_lshlrev_b32_e32 v120, 16, v120
	v_lshlrev_b32_e32 v72, 16, v72
	v_or_b32_sdwa v78, v126, v75 dst_sel:DWORD dst_unused:UNUSED_PAD src0_sel:WORD_1 src1_sel:DWORD
	v_or_b32_sdwa v79, v127, v123 dst_sel:DWORD dst_unused:UNUSED_PAD src0_sel:WORD_1 src1_sel:DWORD
	v_fmac_f32_e32 v134, v74, v74
	v_lshlrev_b32_e32 v121, 16, v121
	v_lshlrev_b32_e32 v73, 16, v73
	v_and_or_b32 v74, v126, s4, v72
	v_and_or_b32 v72, v124, s4, v120
	v_fmac_f32_e32 v134, v75, v75
	v_and_or_b32 v75, v127, s4, v73
	v_and_or_b32 v73, v125, s4, v121
	global_store_dwordx4 v[194:195], v[76:79], off
	global_store_dwordx4 v[196:197], v[72:75], off nt
	v_and_b32_e32 v122, 0xffff0000, v127
	v_and_b32_e32 v76, 0xffff0000, v116
	v_lshlrev_b32_e32 v72, 16, v117
	v_lshlrev_b32_e32 v74, 16, v116
	v_or_b32_sdwa v73, v113, v72 dst_sel:DWORD dst_unused:UNUSED_PAD src0_sel:WORD_0 src1_sel:DWORD
	v_or_b32_sdwa v72, v112, v74 dst_sel:DWORD dst_unused:UNUSED_PAD src0_sel:WORD_0 src1_sel:DWORD
	v_and_b32_e32 v74, 0xffff0000, v117
	v_or_b32_sdwa v75, v113, v74 dst_sel:DWORD dst_unused:UNUSED_PAD src0_sel:WORD_1 src1_sel:DWORD
	v_or_b32_sdwa v74, v112, v76 dst_sel:DWORD dst_unused:UNUSED_PAD src0_sel:WORD_1 src1_sel:DWORD
	v_mov_b32_e32 v76, v68
	v_mov_b32_e32 v77, v70
	v_fmac_f32_e32 v134, v122, v122
	v_pk_add_f32 v[72:73], v[76:77], v[72:73]
	v_mov_b32_e32 v70, v69
	v_fmac_f32_e32 v134, v123, v123
	v_pk_add_f32 v[74:75], v[70:71], v[74:75]
	v_and_b32_e32 v68, 0xffff0000, v72
	v_lshlrev_b32_e32 v70, 16, v119
	v_lshlrev_b32_e32 v76, 16, v118
	v_fmac_f32_e32 v134, v68, v68
	v_and_b32_e32 v68, 0xffff0000, v74
	v_or_b32_sdwa v71, v115, v70 dst_sel:DWORD dst_unused:UNUSED_PAD src0_sel:WORD_0 src1_sel:DWORD
	v_or_b32_sdwa v70, v114, v76 dst_sel:DWORD dst_unused:UNUSED_PAD src0_sel:WORD_0 src1_sel:DWORD
	v_and_b32_e32 v76, 0xffff0000, v119
	v_and_b32_e32 v78, 0xffff0000, v118
	v_fmac_f32_e32 v134, v68, v68
	v_and_b32_e32 v69, 0xffff0000, v73
	v_or_b32_sdwa v77, v115, v76 dst_sel:DWORD dst_unused:UNUSED_PAD src0_sel:WORD_1 src1_sel:DWORD
	v_or_b32_sdwa v76, v114, v78 dst_sel:DWORD dst_unused:UNUSED_PAD src0_sel:WORD_1 src1_sel:DWORD
	v_mov_b32_e32 v78, v64
	v_mov_b32_e32 v79, v66
	v_fmac_f32_e32 v134, v69, v69
	v_and_b32_e32 v69, 0xffff0000, v75
	v_pk_add_f32 v[78:79], v[78:79], v[70:71]
	v_mov_b32_e32 v66, v65
	v_fmac_f32_e32 v134, v69, v69
	v_pk_add_f32 v[64:65], v[66:67], v[76:77]
	v_and_b32_e32 v66, 0xffff0000, v78
	v_and_b32_e32 v67, 0xffff0000, v64
	v_fmac_f32_e32 v134, v66, v66
	v_and_b32_e32 v76, 0xffff0000, v79
	v_fmac_f32_e32 v134, v67, v67
	v_and_b32_e32 v77, 0xffff0000, v65
	v_fmac_f32_e32 v134, v76, v76
	v_fmac_f32_e32 v134, v77, v77
	ds_bpermute_b32 v76, v207, v134
	v_lshlrev_b32_e32 v64, 16, v64
	v_lshlrev_b32_e32 v66, 16, v74
	v_lshlrev_b32_e32 v65, 16, v65
	v_and_or_b32 v74, v78, s4, v64
	s_waitcnt lgkmcnt(0)
	v_add_f32_e32 v64, v134, v76
	v_or_b32_sdwa v70, v78, v67 dst_sel:DWORD dst_unused:UNUSED_PAD src0_sel:WORD_1 src1_sel:DWORD
	v_lshlrev_b32_e32 v67, 16, v75
	v_and_or_b32 v75, v79, s4, v65
	ds_bpermute_b32 v65, v208, v64
	v_or_b32_sdwa v68, v72, v68 dst_sel:DWORD dst_unused:UNUSED_PAD src0_sel:WORD_1 src1_sel:DWORD
	v_or_b32_sdwa v69, v73, v69 dst_sel:DWORD dst_unused:UNUSED_PAD src0_sel:WORD_1 src1_sel:DWORD
	v_or_b32_sdwa v71, v79, v77 dst_sel:DWORD dst_unused:UNUSED_PAD src0_sel:WORD_1 src1_sel:DWORD
	v_and_or_b32 v73, v73, s4, v67
	v_and_or_b32 v72, v72, s4, v66
	global_store_dwordx4 v[194:195], v[68:71], off offset:256
	global_store_dwordx4 v[196:197], v[72:75], off offset:256 nt
	s_and_saveexec_b64 s[22:23], s[6:7]
	s_cbranch_execz .LBB0_787
	v_lshlrev_b64 v[66:67], 6, v[188:189]
	s_lshl_b32 s26, s50, 2
	v_lshl_add_u64 v[66:67], s[2:3], 0, v[66:67]
	s_ashr_i32 s27, s26, 31
	v_lshl_add_u64 v[66:67], s[26:27], 2, v[66:67]
	s_lshl_b32 s24, s46, 2
	v_lshl_add_u64 v[66:67], v[66:67], 0, s[24:25]
	s_waitcnt lgkmcnt(0)
	v_add_f32_e32 v64, v64, v65
	global_store_dword v[66:67], v64, off
.LBB0_787:
	s_or_b64 exec, exec, s[22:23]
	v_add_u32_e32 v112, 0xa0, v184
	v_ashrrev_i32_e32 v113, 31, v112
	s_waitcnt lgkmcnt(0)
	v_lshlrev_b64 v[64:65], 10, v[112:113]
	v_lshl_add_u64 v[64:65], v[64:65], 0, v[182:183]
	v_readlane_b32 s22, v247, 5
	v_lshlrev_b64 v[64:65], 1, v[64:65]
	v_readlane_b32 s23, v247, 6
	s_nop 1
	v_lshl_add_u64 v[114:115], s[22:23], 0, v[64:65]
	v_readlane_b32 s22, v249, 0
	v_readlane_b32 s23, v249, 1
	global_load_dwordx4 v[72:75], v[114:115], off offset:0
	s_nop 1
	v_lshl_add_u64 v[116:117], s[22:23], 0, v[64:65]
	global_load_dwordx4 v[76:79], v[116:117], off offset:0 nt
	global_load_dwordx4 v[68:71], v[114:115], off offset:256
	global_load_dwordx4 v[64:67], v[116:117], off offset:256 nt
	s_waitcnt vmcnt(8)
	s_nop 0
	v_lshlrev_b32_e32 v118, 16, v105
	v_lshlrev_b32_e32 v120, 16, v104
	v_and_b32_e32 v105, 0xffff0000, v105
	v_and_b32_e32 v104, 0xffff0000, v104
	v_or_b32_sdwa v119, v109, v118 dst_sel:DWORD dst_unused:UNUSED_PAD src0_sel:WORD_0 src1_sel:DWORD
	v_or_b32_sdwa v105, v109, v105 dst_sel:DWORD dst_unused:UNUSED_PAD src0_sel:WORD_1 src1_sel:DWORD
	v_or_b32_sdwa v104, v108, v104 dst_sel:DWORD dst_unused:UNUSED_PAD src0_sel:WORD_1 src1_sel:DWORD
	v_mov_b32_e32 v109, v62
	v_mov_b32_e32 v62, v61
	v_or_b32_sdwa v118, v108, v120 dst_sel:DWORD dst_unused:UNUSED_PAD src0_sel:WORD_0 src1_sel:DWORD
	v_mov_b32_e32 v108, v60
	v_pk_add_f32 v[104:105], v[62:63], v[104:105]
	v_pk_add_f32 v[108:109], v[108:109], v[118:119]
	v_and_b32_e32 v61, 0xffff0000, v104
	v_and_b32_e32 v60, 0xffff0000, v108
	v_mul_f32_e32 v118, v61, v61
	v_fmac_f32_e32 v118, v60, v60
	v_and_b32_e32 v60, 0xffff0000, v109
	v_fmac_f32_e32 v118, v60, v60
	v_and_b32_e32 v62, 0xffff0000, v105
	v_fmac_f32_e32 v118, v62, v62
	v_or_b32_sdwa v60, v61, v108 dst_sel:DWORD dst_unused:UNUSED_PAD src0_sel:DWORD src1_sel:WORD_1
	v_or_b32_sdwa v61, v62, v109 dst_sel:DWORD dst_unused:UNUSED_PAD src0_sel:DWORD src1_sel:WORD_1
	v_lshlrev_b32_e32 v62, 16, v107
	v_lshlrev_b32_e32 v119, 16, v106
	v_and_b32_e32 v107, 0xffff0000, v107
	v_and_b32_e32 v106, 0xffff0000, v106
	v_or_b32_sdwa v63, v111, v62 dst_sel:DWORD dst_unused:UNUSED_PAD src0_sel:WORD_0 src1_sel:DWORD
	v_or_b32_sdwa v62, v110, v119 dst_sel:DWORD dst_unused:UNUSED_PAD src0_sel:WORD_0 src1_sel:DWORD
	v_or_b32_sdwa v107, v111, v107 dst_sel:DWORD dst_unused:UNUSED_PAD src0_sel:WORD_1 src1_sel:DWORD
	v_or_b32_sdwa v106, v110, v106 dst_sel:DWORD dst_unused:UNUSED_PAD src0_sel:WORD_1 src1_sel:DWORD
	v_mov_b32_e32 v110, v56
	v_mov_b32_e32 v111, v58
	v_pk_add_f32 v[110:111], v[110:111], v[62:63]
	v_mov_b32_e32 v58, v57
	v_pk_add_f32 v[56:57], v[58:59], v[106:107]
	v_and_b32_e32 v58, 0xffff0000, v110
	v_and_b32_e32 v59, 0xffff0000, v56
	v_fmac_f32_e32 v118, v58, v58
	v_and_b32_e32 v106, 0xffff0000, v111
	v_fmac_f32_e32 v118, v59, v59
	v_and_b32_e32 v107, 0xffff0000, v57
	v_fmac_f32_e32 v118, v106, v106
	v_and_b32_e32 v106, 0xffff, v108
	v_and_b32_e32 v58, 0xffff, v110
	v_or_b32_sdwa v62, v59, v110 dst_sel:DWORD dst_unused:UNUSED_PAD src0_sel:DWORD src1_sel:WORD_1
	v_or_b32_sdwa v63, v107, v111 dst_sel:DWORD dst_unused:UNUSED_PAD src0_sel:DWORD src1_sel:WORD_1
	v_fmac_f32_e32 v118, v107, v107
	v_and_b32_e32 v107, 0xffff, v109
	v_and_b32_e32 v59, 0xffff, v111
	v_lshl_or_b32 v58, v56, 16, v58
	v_lshl_or_b32 v56, v104, 16, v106
	v_lshl_or_b32 v59, v57, 16, v59
	v_lshl_or_b32 v57, v105, 16, v107
	global_store_dwordx4 v[146:147], v[60:63], off
	global_store_dwordx4 v[148:149], v[56:59], off nt
	s_nop 0
	v_and_b32_e32 v60, 0xffff0000, v100
	v_lshlrev_b32_e32 v56, 16, v101
	v_lshlrev_b32_e32 v58, 16, v100
	v_or_b32_sdwa v57, v97, v56 dst_sel:DWORD dst_unused:UNUSED_PAD src0_sel:WORD_0 src1_sel:DWORD
	v_or_b32_sdwa v56, v96, v58 dst_sel:DWORD dst_unused:UNUSED_PAD src0_sel:WORD_0 src1_sel:DWORD
	v_and_b32_e32 v58, 0xffff0000, v101
	v_or_b32_sdwa v59, v97, v58 dst_sel:DWORD dst_unused:UNUSED_PAD src0_sel:WORD_1 src1_sel:DWORD
	v_or_b32_sdwa v58, v96, v60 dst_sel:DWORD dst_unused:UNUSED_PAD src0_sel:WORD_1 src1_sel:DWORD
	v_mov_b32_e32 v60, v52
	v_mov_b32_e32 v61, v54
	v_pk_add_f32 v[56:57], v[60:61], v[56:57]
	v_mov_b32_e32 v54, v53
	v_pk_add_f32 v[60:61], v[54:55], v[58:59]
	v_and_b32_e32 v52, 0xffff0000, v56
	v_lshlrev_b32_e32 v54, 16, v103
	v_lshlrev_b32_e32 v58, 16, v102
	v_fmac_f32_e32 v118, v52, v52
	v_and_b32_e32 v52, 0xffff0000, v60
	v_or_b32_sdwa v55, v99, v54 dst_sel:DWORD dst_unused:UNUSED_PAD src0_sel:WORD_0 src1_sel:DWORD
	v_or_b32_sdwa v54, v98, v58 dst_sel:DWORD dst_unused:UNUSED_PAD src0_sel:WORD_0 src1_sel:DWORD
	v_and_b32_e32 v58, 0xffff0000, v103
	v_and_b32_e32 v62, 0xffff0000, v102
	v_fmac_f32_e32 v118, v52, v52
	v_and_b32_e32 v53, 0xffff0000, v57
	v_or_b32_sdwa v59, v99, v58 dst_sel:DWORD dst_unused:UNUSED_PAD src0_sel:WORD_1 src1_sel:DWORD
	v_or_b32_sdwa v58, v98, v62 dst_sel:DWORD dst_unused:UNUSED_PAD src0_sel:WORD_1 src1_sel:DWORD
	v_mov_b32_e32 v62, v48
	v_mov_b32_e32 v63, v50
	v_fmac_f32_e32 v118, v53, v53
	v_and_b32_e32 v53, 0xffff0000, v61
	v_pk_add_f32 v[62:63], v[62:63], v[54:55]
	v_mov_b32_e32 v50, v49
	v_fmac_f32_e32 v118, v53, v53
	v_pk_add_f32 v[48:49], v[50:51], v[58:59]
	v_and_b32_e32 v50, 0xffff0000, v62
	v_and_b32_e32 v51, 0xffff0000, v48
	v_fmac_f32_e32 v118, v50, v50
	v_and_b32_e32 v58, 0xffff0000, v63
	v_fmac_f32_e32 v118, v51, v51
	v_and_b32_e32 v59, 0xffff0000, v49
	v_fmac_f32_e32 v118, v58, v58
	v_fmac_f32_e32 v118, v59, v59
	v_or_b32_sdwa v52, v52, v56 dst_sel:DWORD dst_unused:UNUSED_PAD src0_sel:DWORD src1_sel:WORD_1
	v_and_b32_e32 v50, 0xffff, v56
	ds_bpermute_b32 v56, v207, v118
	v_or_b32_sdwa v53, v53, v57 dst_sel:DWORD dst_unused:UNUSED_PAD src0_sel:DWORD src1_sel:WORD_1
	v_or_b32_sdwa v54, v51, v62 dst_sel:DWORD dst_unused:UNUSED_PAD src0_sel:DWORD src1_sel:WORD_1
	v_and_b32_e32 v51, 0xffff, v57
	v_and_b32_e32 v57, 0xffff, v62
	v_and_b32_e32 v58, 0xffff, v63
	v_or_b32_sdwa v55, v59, v63 dst_sel:DWORD dst_unused:UNUSED_PAD src0_sel:DWORD src1_sel:WORD_1
	v_lshl_or_b32 v59, v49, 16, v58
	v_lshl_or_b32 v58, v48, 16, v57
	s_waitcnt lgkmcnt(0)
	v_add_f32_e32 v48, v118, v56
	ds_bpermute_b32 v49, v208, v48
	v_lshl_or_b32 v57, v61, 16, v51
	v_lshl_or_b32 v56, v60, 16, v50
	global_store_dwordx4 v[146:147], v[52:55], off offset:256
	global_store_dwordx4 v[148:149], v[56:59], off offset:256 nt
	s_and_saveexec_b64 s[22:23], s[6:7]
	s_cbranch_execz .LBB0_789
	v_lshlrev_b64 v[50:51], 6, v[144:145]
	s_lshl_b32 s26, s50, 2
	v_lshl_add_u64 v[50:51], s[2:3], 0, v[50:51]
	s_ashr_i32 s27, s26, 31
	v_lshl_add_u64 v[50:51], s[26:27], 2, v[50:51]
	s_lshl_b32 s24, s46, 2
	v_lshl_add_u64 v[50:51], v[50:51], 0, s[24:25]
	s_waitcnt lgkmcnt(0)
	v_add_f32_e32 v48, v48, v49
	global_store_dword v[50:51], v48, off
.LBB0_789:
	s_or_b64 exec, exec, s[22:23]
	v_add_u32_e32 v96, 0xb0, v184
	v_ashrrev_i32_e32 v97, 31, v96
	s_waitcnt lgkmcnt(0)
	v_lshlrev_b64 v[48:49], 10, v[96:97]
	v_lshl_add_u64 v[48:49], v[48:49], 0, v[182:183]
	v_readlane_b32 s22, v247, 5
	v_lshlrev_b64 v[48:49], 1, v[48:49]
	v_readlane_b32 s23, v247, 6
	s_nop 1
	v_lshl_add_u64 v[98:99], s[22:23], 0, v[48:49]
	v_readlane_b32 s22, v249, 0
	v_readlane_b32 s23, v249, 1
	global_load_dwordx4 v[56:59], v[98:99], off offset:0
	s_nop 1
	v_lshl_add_u64 v[100:101], s[22:23], 0, v[48:49]
	global_load_dwordx4 v[60:63], v[100:101], off offset:0 nt
	global_load_dwordx4 v[52:55], v[98:99], off offset:256
	global_load_dwordx4 v[48:51], v[100:101], off offset:256 nt
	s_waitcnt vmcnt(8)
	s_nop 0
	v_lshlrev_b32_e32 v102, 16, v89
	v_lshlrev_b32_e32 v104, 16, v88
	v_and_b32_e32 v89, 0xffff0000, v89
	v_and_b32_e32 v88, 0xffff0000, v88
	v_or_b32_sdwa v103, v93, v102 dst_sel:DWORD dst_unused:UNUSED_PAD src0_sel:WORD_0 src1_sel:DWORD
	v_or_b32_sdwa v89, v93, v89 dst_sel:DWORD dst_unused:UNUSED_PAD src0_sel:WORD_1 src1_sel:DWORD
	v_or_b32_sdwa v88, v92, v88 dst_sel:DWORD dst_unused:UNUSED_PAD src0_sel:WORD_1 src1_sel:DWORD
	v_mov_b32_e32 v93, v46
	v_mov_b32_e32 v46, v45
	v_or_b32_sdwa v102, v92, v104 dst_sel:DWORD dst_unused:UNUSED_PAD src0_sel:WORD_0 src1_sel:DWORD
	v_mov_b32_e32 v92, v44
	v_pk_add_f32 v[88:89], v[46:47], v[88:89]
	v_pk_add_f32 v[92:93], v[92:93], v[102:103]
	v_and_b32_e32 v45, 0xffff0000, v88
	v_and_b32_e32 v44, 0xffff0000, v92
	v_mul_f32_e32 v102, v45, v45
	v_fmac_f32_e32 v102, v44, v44
	v_and_b32_e32 v44, 0xffff0000, v93
	v_fmac_f32_e32 v102, v44, v44
	v_and_b32_e32 v46, 0xffff0000, v89
	v_fmac_f32_e32 v102, v46, v46
	v_or_b32_sdwa v44, v45, v92 dst_sel:DWORD dst_unused:UNUSED_PAD src0_sel:DWORD src1_sel:WORD_1
	v_or_b32_sdwa v45, v46, v93 dst_sel:DWORD dst_unused:UNUSED_PAD src0_sel:DWORD src1_sel:WORD_1
	v_lshlrev_b32_e32 v46, 16, v91
	v_lshlrev_b32_e32 v103, 16, v90
	v_and_b32_e32 v91, 0xffff0000, v91
	v_and_b32_e32 v90, 0xffff0000, v90
	v_or_b32_sdwa v47, v95, v46 dst_sel:DWORD dst_unused:UNUSED_PAD src0_sel:WORD_0 src1_sel:DWORD
	v_or_b32_sdwa v46, v94, v103 dst_sel:DWORD dst_unused:UNUSED_PAD src0_sel:WORD_0 src1_sel:DWORD
	v_or_b32_sdwa v91, v95, v91 dst_sel:DWORD dst_unused:UNUSED_PAD src0_sel:WORD_1 src1_sel:DWORD
	v_or_b32_sdwa v90, v94, v90 dst_sel:DWORD dst_unused:UNUSED_PAD src0_sel:WORD_1 src1_sel:DWORD
	v_mov_b32_e32 v94, v40
	v_mov_b32_e32 v95, v42
	v_pk_add_f32 v[94:95], v[94:95], v[46:47]
	v_mov_b32_e32 v42, v41
	v_pk_add_f32 v[40:41], v[42:43], v[90:91]
	v_and_b32_e32 v42, 0xffff0000, v94
	v_and_b32_e32 v43, 0xffff0000, v40
	v_fmac_f32_e32 v102, v42, v42
	v_and_b32_e32 v90, 0xffff0000, v95
	v_fmac_f32_e32 v102, v43, v43
	v_and_b32_e32 v91, 0xffff0000, v41
	v_fmac_f32_e32 v102, v90, v90
	v_and_b32_e32 v90, 0xffff, v92
	v_and_b32_e32 v42, 0xffff, v94
	v_or_b32_sdwa v46, v43, v94 dst_sel:DWORD dst_unused:UNUSED_PAD src0_sel:DWORD src1_sel:WORD_1
	v_or_b32_sdwa v47, v91, v95 dst_sel:DWORD dst_unused:UNUSED_PAD src0_sel:DWORD src1_sel:WORD_1
	v_fmac_f32_e32 v102, v91, v91
	v_and_b32_e32 v91, 0xffff, v93
	v_and_b32_e32 v43, 0xffff, v95
	v_lshl_or_b32 v42, v40, 16, v42
	v_lshl_or_b32 v40, v88, 16, v90
	v_lshl_or_b32 v43, v41, 16, v43
	v_lshl_or_b32 v41, v89, 16, v91
	global_store_dwordx4 v[130:131], v[44:47], off
	global_store_dwordx4 v[132:133], v[40:43], off nt
	s_nop 0
	v_and_b32_e32 v44, 0xffff0000, v84
	v_lshlrev_b32_e32 v40, 16, v85
	v_lshlrev_b32_e32 v42, 16, v84
	v_or_b32_sdwa v41, v81, v40 dst_sel:DWORD dst_unused:UNUSED_PAD src0_sel:WORD_0 src1_sel:DWORD
	v_or_b32_sdwa v40, v80, v42 dst_sel:DWORD dst_unused:UNUSED_PAD src0_sel:WORD_0 src1_sel:DWORD
	v_and_b32_e32 v42, 0xffff0000, v85
	v_or_b32_sdwa v43, v81, v42 dst_sel:DWORD dst_unused:UNUSED_PAD src0_sel:WORD_1 src1_sel:DWORD
	v_or_b32_sdwa v42, v80, v44 dst_sel:DWORD dst_unused:UNUSED_PAD src0_sel:WORD_1 src1_sel:DWORD
	v_mov_b32_e32 v44, v36
	v_mov_b32_e32 v45, v38
	v_pk_add_f32 v[40:41], v[44:45], v[40:41]
	v_mov_b32_e32 v38, v37
	v_pk_add_f32 v[44:45], v[38:39], v[42:43]
	v_and_b32_e32 v36, 0xffff0000, v40
	v_lshlrev_b32_e32 v38, 16, v87
	v_lshlrev_b32_e32 v42, 16, v86
	v_fmac_f32_e32 v102, v36, v36
	v_and_b32_e32 v36, 0xffff0000, v44
	v_or_b32_sdwa v39, v83, v38 dst_sel:DWORD dst_unused:UNUSED_PAD src0_sel:WORD_0 src1_sel:DWORD
	v_or_b32_sdwa v38, v82, v42 dst_sel:DWORD dst_unused:UNUSED_PAD src0_sel:WORD_0 src1_sel:DWORD
	v_and_b32_e32 v42, 0xffff0000, v87
	v_and_b32_e32 v46, 0xffff0000, v86
	v_fmac_f32_e32 v102, v36, v36
	v_and_b32_e32 v37, 0xffff0000, v41
	v_or_b32_sdwa v43, v83, v42 dst_sel:DWORD dst_unused:UNUSED_PAD src0_sel:WORD_1 src1_sel:DWORD
	v_or_b32_sdwa v42, v82, v46 dst_sel:DWORD dst_unused:UNUSED_PAD src0_sel:WORD_1 src1_sel:DWORD
	v_mov_b32_e32 v46, v32
	v_mov_b32_e32 v47, v34
	v_fmac_f32_e32 v102, v37, v37
	v_and_b32_e32 v37, 0xffff0000, v45
	v_pk_add_f32 v[46:47], v[46:47], v[38:39]
	v_mov_b32_e32 v34, v33
	v_fmac_f32_e32 v102, v37, v37
	v_pk_add_f32 v[32:33], v[34:35], v[42:43]
	v_and_b32_e32 v34, 0xffff0000, v46
	v_and_b32_e32 v35, 0xffff0000, v32
	v_fmac_f32_e32 v102, v34, v34
	v_and_b32_e32 v42, 0xffff0000, v47
	v_fmac_f32_e32 v102, v35, v35
	v_and_b32_e32 v43, 0xffff0000, v33
	v_fmac_f32_e32 v102, v42, v42
	v_fmac_f32_e32 v102, v43, v43
	v_or_b32_sdwa v36, v36, v40 dst_sel:DWORD dst_unused:UNUSED_PAD src0_sel:DWORD src1_sel:WORD_1
	v_and_b32_e32 v34, 0xffff, v40
	ds_bpermute_b32 v40, v207, v102
	v_or_b32_sdwa v37, v37, v41 dst_sel:DWORD dst_unused:UNUSED_PAD src0_sel:DWORD src1_sel:WORD_1
	v_or_b32_sdwa v38, v35, v46 dst_sel:DWORD dst_unused:UNUSED_PAD src0_sel:DWORD src1_sel:WORD_1
	v_and_b32_e32 v35, 0xffff, v41
	v_and_b32_e32 v41, 0xffff, v46
	v_and_b32_e32 v42, 0xffff, v47
	v_or_b32_sdwa v39, v43, v47 dst_sel:DWORD dst_unused:UNUSED_PAD src0_sel:DWORD src1_sel:WORD_1
	v_lshl_or_b32 v43, v33, 16, v42
	v_lshl_or_b32 v42, v32, 16, v41
	s_waitcnt lgkmcnt(0)
	v_add_f32_e32 v32, v102, v40
	ds_bpermute_b32 v33, v208, v32
	v_lshl_or_b32 v41, v45, 16, v35
	v_lshl_or_b32 v40, v44, 16, v34
	global_store_dwordx4 v[130:131], v[36:39], off offset:256
	global_store_dwordx4 v[132:133], v[40:43], off offset:256 nt
	s_and_saveexec_b64 s[22:23], s[6:7]
	s_cbranch_execz .LBB0_791
	v_lshlrev_b64 v[34:35], 6, v[128:129]
	s_lshl_b32 s26, s50, 2
	v_lshl_add_u64 v[34:35], s[2:3], 0, v[34:35]
	s_ashr_i32 s27, s26, 31
	v_lshl_add_u64 v[34:35], s[26:27], 2, v[34:35]
	s_lshl_b32 s24, s46, 2
	v_lshl_add_u64 v[34:35], v[34:35], 0, s[24:25]
	s_waitcnt lgkmcnt(0)
	v_add_f32_e32 v32, v32, v33
	global_store_dword v[34:35], v32, off
.LBB0_791:
	s_or_b64 exec, exec, s[22:23]
	s_waitcnt vmcnt(4)
	v_mov_b32_e32 v37, v30
	v_lshlrev_b32_e32 v32, 16, v73
	v_lshlrev_b32_e32 v34, 16, v72
	v_and_b32_e32 v35, 0xffff0000, v73
	s_waitcnt lgkmcnt(0)
	v_or_b32_sdwa v33, v77, v32 dst_sel:DWORD dst_unused:UNUSED_PAD src0_sel:WORD_0 src1_sel:DWORD
	v_or_b32_sdwa v32, v76, v34 dst_sel:DWORD dst_unused:UNUSED_PAD src0_sel:WORD_0 src1_sel:DWORD
	v_and_b32_e32 v34, 0xffff0000, v72
	v_or_b32_sdwa v35, v77, v35 dst_sel:DWORD dst_unused:UNUSED_PAD src0_sel:WORD_1 src1_sel:DWORD
	v_or_b32_sdwa v34, v76, v34 dst_sel:DWORD dst_unused:UNUSED_PAD src0_sel:WORD_1 src1_sel:DWORD
	v_mov_b32_e32 v30, v29
	v_mov_b32_e32 v36, v28
	v_pk_add_f32 v[34:35], v[30:31], v[34:35]
	v_pk_add_f32 v[32:33], v[36:37], v[32:33]
	v_and_b32_e32 v29, 0xffff0000, v34
	v_and_b32_e32 v28, 0xffff0000, v32
	v_mul_f32_e32 v40, v29, v29
	v_fmac_f32_e32 v40, v28, v28
	v_and_b32_e32 v28, 0xffff0000, v33
	v_fmac_f32_e32 v40, v28, v28
	v_and_b32_e32 v30, 0xffff0000, v35
	v_fmac_f32_e32 v40, v30, v30
	v_or_b32_sdwa v28, v29, v32 dst_sel:DWORD dst_unused:UNUSED_PAD src0_sel:DWORD src1_sel:WORD_1
	v_or_b32_sdwa v29, v30, v33 dst_sel:DWORD dst_unused:UNUSED_PAD src0_sel:DWORD src1_sel:WORD_1
	v_lshlrev_b32_e32 v30, 16, v75
	v_lshlrev_b32_e32 v36, 16, v74
	v_or_b32_sdwa v31, v79, v30 dst_sel:DWORD dst_unused:UNUSED_PAD src0_sel:WORD_0 src1_sel:DWORD
	v_or_b32_sdwa v30, v78, v36 dst_sel:DWORD dst_unused:UNUSED_PAD src0_sel:WORD_0 src1_sel:DWORD
	v_and_b32_e32 v36, 0xffff0000, v75
	v_and_b32_e32 v38, 0xffff0000, v74
	v_or_b32_sdwa v37, v79, v36 dst_sel:DWORD dst_unused:UNUSED_PAD src0_sel:WORD_1 src1_sel:DWORD
	v_or_b32_sdwa v36, v78, v38 dst_sel:DWORD dst_unused:UNUSED_PAD src0_sel:WORD_1 src1_sel:DWORD
	v_mov_b32_e32 v38, v24
	v_mov_b32_e32 v39, v26
	v_pk_add_f32 v[38:39], v[38:39], v[30:31]
	v_mov_b32_e32 v26, v25
	v_pk_add_f32 v[24:25], v[26:27], v[36:37]
	v_and_b32_e32 v26, 0xffff0000, v38
	v_and_b32_e32 v27, 0xffff0000, v24
	v_and_b32_e32 v37, 0xffff0000, v25
	v_fmac_f32_e32 v40, v26, v26
	v_and_b32_e32 v32, 0xffff, v32
	v_and_b32_e32 v26, 0xffff, v38
	v_or_b32_sdwa v30, v27, v38 dst_sel:DWORD dst_unused:UNUSED_PAD src0_sel:DWORD src1_sel:WORD_1
	v_or_b32_sdwa v31, v37, v39 dst_sel:DWORD dst_unused:UNUSED_PAD src0_sel:DWORD src1_sel:WORD_1
	v_fmac_f32_e32 v40, v27, v27
	v_and_b32_e32 v33, 0xffff, v33
	v_and_b32_e32 v27, 0xffff, v39
	v_lshl_or_b32 v26, v24, 16, v26
	v_lshl_or_b32 v24, v34, 16, v32
	v_lshl_or_b32 v27, v25, 16, v27
	v_lshl_or_b32 v25, v35, 16, v33
	global_store_dwordx4 v[114:115], v[28:31], off
	global_store_dwordx4 v[116:117], v[24:27], off nt
	v_and_b32_e32 v36, 0xffff0000, v39
	v_and_b32_e32 v28, 0xffff0000, v68
	v_lshlrev_b32_e32 v24, 16, v69
	v_lshlrev_b32_e32 v26, 16, v68
	v_or_b32_sdwa v25, v65, v24 dst_sel:DWORD dst_unused:UNUSED_PAD src0_sel:WORD_0 src1_sel:DWORD
	v_or_b32_sdwa v24, v64, v26 dst_sel:DWORD dst_unused:UNUSED_PAD src0_sel:WORD_0 src1_sel:DWORD
	v_and_b32_e32 v26, 0xffff0000, v69
	v_or_b32_sdwa v27, v65, v26 dst_sel:DWORD dst_unused:UNUSED_PAD src0_sel:WORD_1 src1_sel:DWORD
	v_or_b32_sdwa v26, v64, v28 dst_sel:DWORD dst_unused:UNUSED_PAD src0_sel:WORD_1 src1_sel:DWORD
	v_mov_b32_e32 v28, v20
	v_mov_b32_e32 v29, v22
	v_fmac_f32_e32 v40, v36, v36
	v_pk_add_f32 v[24:25], v[28:29], v[24:25]
	v_mov_b32_e32 v22, v21
	v_fmac_f32_e32 v40, v37, v37
	v_pk_add_f32 v[28:29], v[22:23], v[26:27]
	v_and_b32_e32 v20, 0xffff0000, v24
	v_lshlrev_b32_e32 v22, 16, v71
	v_lshlrev_b32_e32 v26, 16, v70
	v_fmac_f32_e32 v40, v20, v20
	v_and_b32_e32 v20, 0xffff0000, v28
	v_or_b32_sdwa v23, v67, v22 dst_sel:DWORD dst_unused:UNUSED_PAD src0_sel:WORD_0 src1_sel:DWORD
	v_or_b32_sdwa v22, v66, v26 dst_sel:DWORD dst_unused:UNUSED_PAD src0_sel:WORD_0 src1_sel:DWORD
	v_and_b32_e32 v26, 0xffff0000, v71
	v_and_b32_e32 v30, 0xffff0000, v70
	v_fmac_f32_e32 v40, v20, v20
	v_and_b32_e32 v21, 0xffff0000, v25
	v_or_b32_sdwa v27, v67, v26 dst_sel:DWORD dst_unused:UNUSED_PAD src0_sel:WORD_1 src1_sel:DWORD
	v_or_b32_sdwa v26, v66, v30 dst_sel:DWORD dst_unused:UNUSED_PAD src0_sel:WORD_1 src1_sel:DWORD
	v_mov_b32_e32 v30, v16
	v_mov_b32_e32 v31, v18
	v_fmac_f32_e32 v40, v21, v21
	v_and_b32_e32 v21, 0xffff0000, v29
	v_pk_add_f32 v[30:31], v[30:31], v[22:23]
	v_mov_b32_e32 v18, v17
	v_fmac_f32_e32 v40, v21, v21
	v_pk_add_f32 v[16:17], v[18:19], v[26:27]
	v_and_b32_e32 v18, 0xffff0000, v30
	v_and_b32_e32 v19, 0xffff0000, v16
	v_fmac_f32_e32 v40, v18, v18
	v_and_b32_e32 v26, 0xffff0000, v31
	v_fmac_f32_e32 v40, v19, v19
	v_and_b32_e32 v27, 0xffff0000, v17
	v_fmac_f32_e32 v40, v26, v26
	v_fmac_f32_e32 v40, v27, v27
	v_or_b32_sdwa v20, v20, v24 dst_sel:DWORD dst_unused:UNUSED_PAD src0_sel:DWORD src1_sel:WORD_1
	v_and_b32_e32 v18, 0xffff, v24
	ds_bpermute_b32 v24, v207, v40
	v_or_b32_sdwa v21, v21, v25 dst_sel:DWORD dst_unused:UNUSED_PAD src0_sel:DWORD src1_sel:WORD_1
	v_or_b32_sdwa v22, v19, v30 dst_sel:DWORD dst_unused:UNUSED_PAD src0_sel:DWORD src1_sel:WORD_1
	v_and_b32_e32 v19, 0xffff, v25
	v_and_b32_e32 v25, 0xffff, v30
	v_and_b32_e32 v26, 0xffff, v31
	v_or_b32_sdwa v23, v27, v31 dst_sel:DWORD dst_unused:UNUSED_PAD src0_sel:DWORD src1_sel:WORD_1
	v_lshl_or_b32 v27, v17, 16, v26
	v_lshl_or_b32 v26, v16, 16, v25
	s_waitcnt lgkmcnt(0)
	v_add_f32_e32 v16, v40, v24
	ds_bpermute_b32 v17, v208, v16
	v_lshl_or_b32 v25, v29, 16, v19
	v_lshl_or_b32 v24, v28, 16, v18
	global_store_dwordx4 v[114:115], v[20:23], off offset:256
	global_store_dwordx4 v[116:117], v[24:27], off offset:256 nt
	s_and_saveexec_b64 s[22:23], s[6:7]
	s_cbranch_execz .LBB0_793
	v_lshlrev_b64 v[18:19], 6, v[112:113]
	s_lshl_b32 s26, s50, 2
	v_lshl_add_u64 v[18:19], s[2:3], 0, v[18:19]
	s_ashr_i32 s27, s26, 31
	v_lshl_add_u64 v[18:19], s[26:27], 2, v[18:19]
	s_lshl_b32 s24, s46, 2
	v_lshl_add_u64 v[18:19], v[18:19], 0, s[24:25]
	s_waitcnt lgkmcnt(0)
	v_add_f32_e32 v16, v16, v17
	global_store_dword v[18:19], v16, off
.LBB0_793:
	s_or_b64 exec, exec, s[22:23]
	s_waitcnt vmcnt(0)
	v_mov_b32_e32 v21, v14
	v_lshlrev_b32_e32 v16, 16, v57
	v_lshlrev_b32_e32 v18, 16, v56
	v_and_b32_e32 v19, 0xffff0000, v57
	s_waitcnt lgkmcnt(0)
	v_or_b32_sdwa v17, v61, v16 dst_sel:DWORD dst_unused:UNUSED_PAD src0_sel:WORD_0 src1_sel:DWORD
	v_or_b32_sdwa v16, v60, v18 dst_sel:DWORD dst_unused:UNUSED_PAD src0_sel:WORD_0 src1_sel:DWORD
	v_and_b32_e32 v18, 0xffff0000, v56
	v_or_b32_sdwa v19, v61, v19 dst_sel:DWORD dst_unused:UNUSED_PAD src0_sel:WORD_1 src1_sel:DWORD
	v_or_b32_sdwa v18, v60, v18 dst_sel:DWORD dst_unused:UNUSED_PAD src0_sel:WORD_1 src1_sel:DWORD
	v_mov_b32_e32 v14, v13
	v_mov_b32_e32 v20, v12
	v_pk_add_f32 v[18:19], v[14:15], v[18:19]
	v_pk_add_f32 v[16:17], v[20:21], v[16:17]
	v_and_b32_e32 v13, 0xffff0000, v18
	v_and_b32_e32 v12, 0xffff0000, v16
	v_mul_f32_e32 v24, v13, v13
	v_fmac_f32_e32 v24, v12, v12
	v_and_b32_e32 v12, 0xffff0000, v17
	v_fmac_f32_e32 v24, v12, v12
	v_and_b32_e32 v14, 0xffff0000, v19
	v_fmac_f32_e32 v24, v14, v14
	v_or_b32_sdwa v12, v13, v16 dst_sel:DWORD dst_unused:UNUSED_PAD src0_sel:DWORD src1_sel:WORD_1
	v_or_b32_sdwa v13, v14, v17 dst_sel:DWORD dst_unused:UNUSED_PAD src0_sel:DWORD src1_sel:WORD_1
	v_lshlrev_b32_e32 v14, 16, v59
	v_lshlrev_b32_e32 v20, 16, v58
	v_or_b32_sdwa v15, v63, v14 dst_sel:DWORD dst_unused:UNUSED_PAD src0_sel:WORD_0 src1_sel:DWORD
	v_or_b32_sdwa v14, v62, v20 dst_sel:DWORD dst_unused:UNUSED_PAD src0_sel:WORD_0 src1_sel:DWORD
	v_and_b32_e32 v20, 0xffff0000, v59
	v_and_b32_e32 v22, 0xffff0000, v58
	v_or_b32_sdwa v21, v63, v20 dst_sel:DWORD dst_unused:UNUSED_PAD src0_sel:WORD_1 src1_sel:DWORD
	v_or_b32_sdwa v20, v62, v22 dst_sel:DWORD dst_unused:UNUSED_PAD src0_sel:WORD_1 src1_sel:DWORD
	v_mov_b32_e32 v22, v8
	v_mov_b32_e32 v23, v10
	v_pk_add_f32 v[22:23], v[22:23], v[14:15]
	v_mov_b32_e32 v10, v9
	v_pk_add_f32 v[8:9], v[10:11], v[20:21]
	v_and_b32_e32 v10, 0xffff0000, v22
	v_and_b32_e32 v11, 0xffff0000, v8
	v_and_b32_e32 v21, 0xffff0000, v9
	v_fmac_f32_e32 v24, v10, v10
	v_and_b32_e32 v16, 0xffff, v16
	v_and_b32_e32 v10, 0xffff, v22
	v_or_b32_sdwa v14, v11, v22 dst_sel:DWORD dst_unused:UNUSED_PAD src0_sel:DWORD src1_sel:WORD_1
	v_or_b32_sdwa v15, v21, v23 dst_sel:DWORD dst_unused:UNUSED_PAD src0_sel:DWORD src1_sel:WORD_1
	v_fmac_f32_e32 v24, v11, v11
	v_and_b32_e32 v17, 0xffff, v17
	v_and_b32_e32 v11, 0xffff, v23
	v_lshl_or_b32 v10, v8, 16, v10
	v_lshl_or_b32 v8, v18, 16, v16
	v_lshl_or_b32 v11, v9, 16, v11
	v_lshl_or_b32 v9, v19, 16, v17
	global_store_dwordx4 v[98:99], v[12:15], off
	global_store_dwordx4 v[100:101], v[8:11], off nt
	v_and_b32_e32 v20, 0xffff0000, v23
	v_and_b32_e32 v12, 0xffff0000, v52
	v_lshlrev_b32_e32 v8, 16, v53
	v_lshlrev_b32_e32 v10, 16, v52
	v_or_b32_sdwa v9, v49, v8 dst_sel:DWORD dst_unused:UNUSED_PAD src0_sel:WORD_0 src1_sel:DWORD
	v_or_b32_sdwa v8, v48, v10 dst_sel:DWORD dst_unused:UNUSED_PAD src0_sel:WORD_0 src1_sel:DWORD
	v_and_b32_e32 v10, 0xffff0000, v53
	v_or_b32_sdwa v11, v49, v10 dst_sel:DWORD dst_unused:UNUSED_PAD src0_sel:WORD_1 src1_sel:DWORD
	v_or_b32_sdwa v10, v48, v12 dst_sel:DWORD dst_unused:UNUSED_PAD src0_sel:WORD_1 src1_sel:DWORD
	v_mov_b32_e32 v12, v4
	v_mov_b32_e32 v13, v6
	v_fmac_f32_e32 v24, v20, v20
	v_pk_add_f32 v[8:9], v[12:13], v[8:9]
	v_mov_b32_e32 v6, v5
	v_fmac_f32_e32 v24, v21, v21
	v_pk_add_f32 v[12:13], v[6:7], v[10:11]
	v_and_b32_e32 v4, 0xffff0000, v8
	v_lshlrev_b32_e32 v6, 16, v55
	v_lshlrev_b32_e32 v10, 16, v54
	v_fmac_f32_e32 v24, v4, v4
	v_and_b32_e32 v4, 0xffff0000, v12
	v_or_b32_sdwa v7, v51, v6 dst_sel:DWORD dst_unused:UNUSED_PAD src0_sel:WORD_0 src1_sel:DWORD
	v_or_b32_sdwa v6, v50, v10 dst_sel:DWORD dst_unused:UNUSED_PAD src0_sel:WORD_0 src1_sel:DWORD
	v_and_b32_e32 v10, 0xffff0000, v55
	v_and_b32_e32 v14, 0xffff0000, v54
	v_fmac_f32_e32 v24, v4, v4
	v_and_b32_e32 v5, 0xffff0000, v9
	v_or_b32_sdwa v11, v51, v10 dst_sel:DWORD dst_unused:UNUSED_PAD src0_sel:WORD_1 src1_sel:DWORD
	v_or_b32_sdwa v10, v50, v14 dst_sel:DWORD dst_unused:UNUSED_PAD src0_sel:WORD_1 src1_sel:DWORD
	v_mov_b32_e32 v14, v0
	v_mov_b32_e32 v15, v2
	v_fmac_f32_e32 v24, v5, v5
	v_and_b32_e32 v5, 0xffff0000, v13
	v_pk_add_f32 v[14:15], v[14:15], v[6:7]
	v_mov_b32_e32 v2, v1
	v_fmac_f32_e32 v24, v5, v5
	v_pk_add_f32 v[0:1], v[2:3], v[10:11]
	v_and_b32_e32 v2, 0xffff0000, v14
	v_and_b32_e32 v3, 0xffff0000, v0
	v_fmac_f32_e32 v24, v2, v2
	v_and_b32_e32 v10, 0xffff0000, v15
	v_fmac_f32_e32 v24, v3, v3
	v_and_b32_e32 v11, 0xffff0000, v1
	v_fmac_f32_e32 v24, v10, v10
	v_fmac_f32_e32 v24, v11, v11
	v_or_b32_sdwa v4, v4, v8 dst_sel:DWORD dst_unused:UNUSED_PAD src0_sel:DWORD src1_sel:WORD_1
	v_and_b32_e32 v2, 0xffff, v8
	ds_bpermute_b32 v8, v207, v24
	v_or_b32_sdwa v5, v5, v9 dst_sel:DWORD dst_unused:UNUSED_PAD src0_sel:DWORD src1_sel:WORD_1
	v_or_b32_sdwa v6, v3, v14 dst_sel:DWORD dst_unused:UNUSED_PAD src0_sel:DWORD src1_sel:WORD_1
	v_and_b32_e32 v3, 0xffff, v9
	v_and_b32_e32 v9, 0xffff, v14
	v_and_b32_e32 v10, 0xffff, v15
	v_or_b32_sdwa v7, v11, v15 dst_sel:DWORD dst_unused:UNUSED_PAD src0_sel:DWORD src1_sel:WORD_1
	v_lshl_or_b32 v11, v1, 16, v10
	v_lshl_or_b32 v10, v0, 16, v9
	s_waitcnt lgkmcnt(0)
	v_add_f32_e32 v0, v24, v8
	ds_bpermute_b32 v1, v208, v0
	v_lshl_or_b32 v9, v13, 16, v3
	v_lshl_or_b32 v8, v12, 16, v2
	global_store_dwordx4 v[98:99], v[4:7], off offset:256
	global_store_dwordx4 v[100:101], v[8:11], off offset:256 nt
	s_and_saveexec_b64 s[22:23], s[6:7]
	s_cbranch_execz .LBB0_795
	v_lshlrev_b64 v[2:3], 6, v[96:97]
	s_lshl_b32 s26, s50, 2
	v_lshl_add_u64 v[2:3], s[2:3], 0, v[2:3]
	s_ashr_i32 s27, s26, 31
	v_lshl_add_u64 v[2:3], s[26:27], 2, v[2:3]
	s_lshl_b32 s24, s46, 2
	v_lshl_add_u64 v[2:3], v[2:3], 0, s[24:25]
	s_waitcnt lgkmcnt(0)
	v_add_f32_e32 v0, v0, v1
	global_store_dword v[2:3], v0, off

.LBB0_989:
	v_lshl_add_u32 v192, s24, 8, v171
	v_lshl_or_b32 v190, s52, 8, v229
	v_ashrrev_i32_e32 v193, 31, v192
	v_lshlrev_b64 v[128:129], 10, v[192:193]
	v_ashrrev_i32_e32 v191, 31, v190
	v_lshl_add_u64 v[240:241], v[128:129], 0, v[190:191]
	v_readlane_b32 s8, v247, 5
	v_lshlrev_b64 v[128:129], 1, v[240:241]
	v_readlane_b32 s9, v247, 6
	v_readlane_b32 s34, v249, 0
	v_or_b32_e32 v202, 16, v192
	v_lshl_add_u64 v[210:211], s[8:9], 0, v[128:129]
	v_readlane_b32 s35, v249, 1
	global_load_dwordx4 v[232:235], v[210:211], off offset:0
	v_ashrrev_i32_e32 v203, 31, v202
	v_or_b32_e32 v194, 32, v192
	v_lshl_add_u64 v[212:213], s[34:35], 0, v[128:129]
	global_load_dwordx4 v[236:239], v[212:213], off offset:0 nt
	v_lshlrev_b64 v[128:129], 10, v[202:203]
	global_load_dwordx4 v[164:167], v[210:211], off offset:256
	v_lshl_add_u64 v[208:209], v[128:129], 0, v[190:191]
	global_load_dwordx4 v[160:163], v[212:213], off offset:256 nt
	v_lshlrev_b64 v[128:129], 1, v[208:209]
	v_lshl_add_u64 v[204:205], s[8:9], 0, v[128:129]
	global_load_dwordx4 v[152:155], v[204:205], off offset:0
	v_ashrrev_i32_e32 v195, 31, v194
	v_lshl_add_u64 v[206:207], s[34:35], 0, v[128:129]
	global_load_dwordx4 v[156:159], v[206:207], off offset:0 nt
	v_lshlrev_b64 v[128:129], 10, v[194:195]
	global_load_dwordx4 v[148:151], v[204:205], off offset:256
	v_lshl_add_u64 v[200:201], v[128:129], 0, v[190:191]
	global_load_dwordx4 v[144:147], v[206:207], off offset:256 nt
	v_lshlrev_b64 v[128:129], 1, v[200:201]
	v_lshl_add_u64 v[196:197], s[8:9], 0, v[128:129]
	global_load_dwordx4 v[136:139], v[196:197], off offset:0
	v_lshl_add_u64 v[198:199], s[34:35], 0, v[128:129]
	global_load_dwordx4 v[140:143], v[198:199], off offset:0 nt
	global_load_dwordx4 v[132:135], v[196:197], off offset:256
	global_load_dwordx4 v[128:131], v[198:199], off offset:256 nt
	s_waitcnt vmcnt(8)
	s_andn2_b64 vcc, exec, s[14:15]
	v_lshlrev_b32_e32 v214, 16, v233
	v_lshlrev_b32_e32 v231, 16, v232
	v_or_b32_sdwa v215, v237, v214 dst_sel:DWORD dst_unused:UNUSED_PAD src0_sel:WORD_0 src1_sel:DWORD
	v_or_b32_sdwa v214, v236, v231 dst_sel:DWORD dst_unused:UNUSED_PAD src0_sel:WORD_0 src1_sel:DWORD
	v_and_b32_e32 v231, 0xffff0000, v233
	v_and_b32_e32 v232, 0xffff0000, v232
	v_or_b32_sdwa v233, v237, v231 dst_sel:DWORD dst_unused:UNUSED_PAD src0_sel:WORD_1 src1_sel:DWORD
	v_or_b32_sdwa v232, v236, v232 dst_sel:DWORD dst_unused:UNUSED_PAD src0_sel:WORD_1 src1_sel:DWORD
	v_mov_b32_e32 v236, v124
	v_mov_b32_e32 v237, v126
	v_mov_b32_e32 v126, v125
	v_lshlrev_b32_e32 v124, 16, v235
	v_lshlrev_b32_e32 v231, 16, v234
	v_pk_add_f32 v[126:127], v[126:127], v[232:233]
	v_or_b32_sdwa v125, v239, v124 dst_sel:DWORD dst_unused:UNUSED_PAD src0_sel:WORD_0 src1_sel:DWORD
	v_or_b32_sdwa v124, v238, v231 dst_sel:DWORD dst_unused:UNUSED_PAD src0_sel:WORD_0 src1_sel:DWORD
	v_and_b32_e32 v231, 0xffff0000, v235
	v_and_b32_e32 v232, 0xffff0000, v234
	v_or_b32_sdwa v233, v239, v231 dst_sel:DWORD dst_unused:UNUSED_PAD src0_sel:WORD_1 src1_sel:DWORD
	v_or_b32_sdwa v232, v238, v232 dst_sel:DWORD dst_unused:UNUSED_PAD src0_sel:WORD_1 src1_sel:DWORD
	v_mov_b32_e32 v234, v120
	v_mov_b32_e32 v235, v122
	v_mov_b32_e32 v122, v121
	v_cndmask_b32_e64 v120, 0, 1, s[14:15]
	v_pk_add_f32 v[214:215], v[236:237], v[214:215]
	v_pk_add_f32 v[124:125], v[234:235], v[124:125]
	v_pk_add_f32 v[122:123], v[122:123], v[232:233]
	v_cmp_ne_u32_e64 s[8:9], 1, v120
	v_lshl_add_u64 v[120:121], v[240:241], 2, s[2:3]
	s_cbranch_vccnz .LBB0_991
	v_mov_b32_e32 v232, v214
	v_mov_b32_e32 v233, v126
	v_mov_b32_e32 v234, v215
	v_mov_b32_e32 v235, v127
	global_store_dwordx4 v[120:121], v[232:235], off
	s_mov_b64 s[34:35], 0
	s_nop 0
	v_mov_b32_e32 v232, v124
	v_mov_b32_e32 v233, v122
	v_mov_b32_e32 v234, v125
	v_mov_b32_e32 v235, v123
	global_store_dwordx4 v[120:121], v[232:235], off offset:16
	s_branch .LBB0_992

.LBB0_992:
	s_nop 0
	v_and_b32_e32 v234, 0xffff0000, v126
	v_and_b32_e32 v233, 0xffff0000, v127
	v_and_b32_e32 v231, 0xffff0000, v122
	s_andn2_b64 vcc, exec, s[34:35]
	v_and_b32_e32 v232, 0xffff0000, v123
	s_cbranch_vccnz .LBB0_994
	v_or_b32_sdwa v236, v214, v234 dst_sel:DWORD dst_unused:UNUSED_PAD src0_sel:WORD_1 src1_sel:DWORD
	v_or_b32_sdwa v237, v215, v233 dst_sel:DWORD dst_unused:UNUSED_PAD src0_sel:WORD_1 src1_sel:DWORD
	v_or_b32_sdwa v238, v124, v231 dst_sel:DWORD dst_unused:UNUSED_PAD src0_sel:WORD_1 src1_sel:DWORD
	v_or_b32_sdwa v239, v125, v232 dst_sel:DWORD dst_unused:UNUSED_PAD src0_sel:WORD_1 src1_sel:DWORD
	v_lshlrev_b32_e32 v126, 16, v126
	v_lshlrev_b32_e32 v127, 16, v127
	v_lshlrev_b32_e32 v122, 16, v122
	v_lshlrev_b32_e32 v123, 16, v123
	s_mov_b32 s4, 0xffff
	v_and_or_b32 v243, v125, s4, v123
	v_and_or_b32 v242, v124, s4, v122
	v_and_or_b32 v241, v215, s4, v127
	v_and_or_b32 v240, v214, s4, v126
	global_store_dwordx4 v[210:211], v[236:239], off
	global_store_dwordx4 v[212:213], v[240:243], off nt

.LBB0_997:
	v_and_b32_e32 v121, 0xffff0000, v118
	v_and_b32_e32 v120, 0xffff0000, v119
	v_and_b32_e32 v114, 0xffff0000, v112
	s_andn2_b64 vcc, exec, s[34:35]
	v_and_b32_e32 v115, 0xffff0000, v113
	s_cbranch_vccnz .LBB0_999
	v_or_b32_sdwa v160, v122, v121 dst_sel:DWORD dst_unused:UNUSED_PAD src0_sel:WORD_1 src1_sel:DWORD
	v_or_b32_sdwa v161, v123, v120 dst_sel:DWORD dst_unused:UNUSED_PAD src0_sel:WORD_1 src1_sel:DWORD
	v_or_b32_sdwa v162, v116, v114 dst_sel:DWORD dst_unused:UNUSED_PAD src0_sel:WORD_1 src1_sel:DWORD
	v_or_b32_sdwa v163, v117, v115 dst_sel:DWORD dst_unused:UNUSED_PAD src0_sel:WORD_1 src1_sel:DWORD
	v_lshlrev_b32_e32 v118, 16, v118
	v_lshlrev_b32_e32 v119, 16, v119
	v_lshlrev_b32_e32 v112, 16, v112
	v_lshlrev_b32_e32 v113, 16, v113
	s_mov_b32 s4, 0xffff
	v_and_or_b32 v167, v117, s4, v113
	v_and_or_b32 v166, v116, s4, v112
	v_and_or_b32 v165, v123, s4, v119
	v_and_or_b32 v164, v122, s4, v118
	global_store_dwordx4 v[210:211], v[160:163], off offset:256
	global_store_dwordx4 v[212:213], v[164:167], off offset:256 nt

.LBB0_1001:
	s_or_b64 exec, exec, s[34:35]
	v_or_b32_e32 v160, 48, v192
	v_ashrrev_i32_e32 v161, 31, v160
	s_waitcnt lgkmcnt(0)
	v_lshlrev_b64 v[112:113], 10, v[160:161]
	v_lshl_add_u64 v[166:167], v[112:113], 0, v[190:191]
	v_readlane_b32 s34, v247, 5
	v_lshlrev_b64 v[112:113], 1, v[166:167]
	v_readlane_b32 s35, v247, 6
	s_and_b64 vcc, exec, s[8:9]
	s_nop 0
	v_lshl_add_u64 v[162:163], s[34:35], 0, v[112:113]
	v_readlane_b32 s34, v249, 0
	v_readlane_b32 s35, v249, 1
	global_load_dwordx4 v[120:123], v[162:163], off offset:0
	s_nop 1
	v_lshl_add_u64 v[164:165], s[34:35], 0, v[112:113]
	global_load_dwordx4 v[124:127], v[164:165], off offset:0 nt
	global_load_dwordx4 v[116:119], v[162:163], off offset:256
	global_load_dwordx4 v[112:115], v[164:165], off offset:256 nt
	s_waitcnt vmcnt(8)
	s_nop 0
	v_lshlrev_b32_e32 v193, 16, v153
	v_lshlrev_b32_e32 v212, 16, v152
	v_and_b32_e32 v153, 0xffff0000, v153
	v_and_b32_e32 v152, 0xffff0000, v152
	v_or_b32_sdwa v213, v157, v193 dst_sel:DWORD dst_unused:UNUSED_PAD src0_sel:WORD_0 src1_sel:DWORD
	v_or_b32_sdwa v212, v156, v212 dst_sel:DWORD dst_unused:UNUSED_PAD src0_sel:WORD_0 src1_sel:DWORD
	v_or_b32_sdwa v157, v157, v153 dst_sel:DWORD dst_unused:UNUSED_PAD src0_sel:WORD_1 src1_sel:DWORD
	v_or_b32_sdwa v156, v156, v152 dst_sel:DWORD dst_unused:UNUSED_PAD src0_sel:WORD_1 src1_sel:DWORD
	v_mov_b32_e32 v153, v110
	v_mov_b32_e32 v110, v109
	v_mov_b32_e32 v152, v108
	v_pk_add_f32 v[110:111], v[110:111], v[156:157]
	v_lshlrev_b32_e32 v108, 16, v155
	v_lshlrev_b32_e32 v156, 16, v154
	v_and_b32_e32 v155, 0xffff0000, v155
	v_and_b32_e32 v154, 0xffff0000, v154
	v_or_b32_sdwa v109, v159, v108 dst_sel:DWORD dst_unused:UNUSED_PAD src0_sel:WORD_0 src1_sel:DWORD
	v_or_b32_sdwa v108, v158, v156 dst_sel:DWORD dst_unused:UNUSED_PAD src0_sel:WORD_0 src1_sel:DWORD
	v_or_b32_sdwa v155, v159, v155 dst_sel:DWORD dst_unused:UNUSED_PAD src0_sel:WORD_1 src1_sel:DWORD
	v_or_b32_sdwa v154, v158, v154 dst_sel:DWORD dst_unused:UNUSED_PAD src0_sel:WORD_1 src1_sel:DWORD
	v_mov_b32_e32 v156, v104
	v_mov_b32_e32 v157, v106
	v_mov_b32_e32 v106, v105
	v_pk_add_f32 v[152:153], v[152:153], v[212:213]
	v_pk_add_f32 v[108:109], v[156:157], v[108:109]
	v_pk_add_f32 v[106:107], v[106:107], v[154:155]
	v_lshl_add_u64 v[104:105], v[208:209], 2, s[2:3]
	s_cbranch_vccnz .LBB0_1003
	v_mov_b32_e32 v154, v152
	v_mov_b32_e32 v155, v110
	v_mov_b32_e32 v156, v153
	v_mov_b32_e32 v157, v111
	global_store_dwordx4 v[104:105], v[154:157], off
	s_mov_b64 s[34:35], 0
	s_nop 0
	v_mov_b32_e32 v154, v108
	v_mov_b32_e32 v155, v106
	v_mov_b32_e32 v156, v109
	v_mov_b32_e32 v157, v107
	global_store_dwordx4 v[104:105], v[154:157], off offset:16
	s_branch .LBB0_1004

.LBB0_1004:
	s_nop 0
	v_and_b32_e32 v157, 0xffff0000, v110
	v_and_b32_e32 v156, 0xffff0000, v111
	v_and_b32_e32 v154, 0xffff0000, v106
	s_andn2_b64 vcc, exec, s[34:35]
	v_and_b32_e32 v155, 0xffff0000, v107
	s_cbranch_vccnz .LBB0_1006
	v_or_b32_sdwa v212, v152, v157 dst_sel:DWORD dst_unused:UNUSED_PAD src0_sel:WORD_1 src1_sel:DWORD
	v_or_b32_sdwa v213, v153, v156 dst_sel:DWORD dst_unused:UNUSED_PAD src0_sel:WORD_1 src1_sel:DWORD
	v_or_b32_sdwa v214, v108, v154 dst_sel:DWORD dst_unused:UNUSED_PAD src0_sel:WORD_1 src1_sel:DWORD
	v_or_b32_sdwa v215, v109, v155 dst_sel:DWORD dst_unused:UNUSED_PAD src0_sel:WORD_1 src1_sel:DWORD
	v_lshlrev_b32_e32 v110, 16, v110
	v_lshlrev_b32_e32 v111, 16, v111
	v_lshlrev_b32_e32 v106, 16, v106
	v_lshlrev_b32_e32 v107, 16, v107
	s_mov_b32 s4, 0xffff
	v_and_or_b32 v235, v109, s4, v107
	v_and_or_b32 v234, v108, s4, v106
	v_and_or_b32 v233, v153, s4, v111
	v_and_or_b32 v232, v152, s4, v110
	global_store_dwordx4 v[204:205], v[212:215], off
	global_store_dwordx4 v[206:207], v[232:235], off nt

.LBB0_1009:
	v_and_b32_e32 v105, 0xffff0000, v102
	v_and_b32_e32 v104, 0xffff0000, v103
	v_and_b32_e32 v98, 0xffff0000, v96
	s_andn2_b64 vcc, exec, s[34:35]
	v_and_b32_e32 v99, 0xffff0000, v97
	s_cbranch_vccnz .LBB0_1011
	v_or_b32_sdwa v144, v106, v105 dst_sel:DWORD dst_unused:UNUSED_PAD src0_sel:WORD_1 src1_sel:DWORD
	v_or_b32_sdwa v145, v107, v104 dst_sel:DWORD dst_unused:UNUSED_PAD src0_sel:WORD_1 src1_sel:DWORD
	v_or_b32_sdwa v146, v100, v98 dst_sel:DWORD dst_unused:UNUSED_PAD src0_sel:WORD_1 src1_sel:DWORD
	v_or_b32_sdwa v147, v101, v99 dst_sel:DWORD dst_unused:UNUSED_PAD src0_sel:WORD_1 src1_sel:DWORD
	v_lshlrev_b32_e32 v102, 16, v102
	v_lshlrev_b32_e32 v103, 16, v103
	v_lshlrev_b32_e32 v96, 16, v96
	v_lshlrev_b32_e32 v97, 16, v97
	s_mov_b32 s4, 0xffff
	v_and_or_b32 v151, v101, s4, v97
	v_and_or_b32 v150, v100, s4, v96
	v_and_or_b32 v149, v107, s4, v103
	v_and_or_b32 v148, v106, s4, v102
	global_store_dwordx4 v[204:205], v[144:147], off offset:256
	global_store_dwordx4 v[206:207], v[148:151], off offset:256 nt

.LBB0_1013:
	s_or_b64 exec, exec, s[34:35]
	v_add_u32_e32 v144, 0x80, v192
	v_ashrrev_i32_e32 v145, 31, v144
	s_waitcnt lgkmcnt(0)
	v_lshlrev_b64 v[96:97], 10, v[144:145]
	v_lshl_add_u64 v[150:151], v[96:97], 0, v[190:191]
	v_readlane_b32 s34, v247, 5
	v_lshlrev_b64 v[96:97], 1, v[150:151]
	v_readlane_b32 s35, v247, 6
	s_and_b64 vcc, exec, s[8:9]
	s_nop 0
	v_lshl_add_u64 v[146:147], s[34:35], 0, v[96:97]
	v_readlane_b32 s34, v249, 0
	v_readlane_b32 s35, v249, 1
	global_load_dwordx4 v[104:107], v[146:147], off offset:0
	s_nop 1
	v_lshl_add_u64 v[148:149], s[34:35], 0, v[96:97]
	global_load_dwordx4 v[108:111], v[148:149], off offset:0 nt
	global_load_dwordx4 v[100:103], v[146:147], off offset:256
	global_load_dwordx4 v[96:99], v[148:149], off offset:256 nt
	s_waitcnt vmcnt(8)
	s_nop 0
	v_lshlrev_b32_e32 v152, 16, v137
	v_lshlrev_b32_e32 v154, 16, v136
	v_and_b32_e32 v137, 0xffff0000, v137
	v_and_b32_e32 v136, 0xffff0000, v136
	v_or_b32_sdwa v153, v141, v152 dst_sel:DWORD dst_unused:UNUSED_PAD src0_sel:WORD_0 src1_sel:DWORD
	v_or_b32_sdwa v152, v140, v154 dst_sel:DWORD dst_unused:UNUSED_PAD src0_sel:WORD_0 src1_sel:DWORD
	v_or_b32_sdwa v141, v141, v137 dst_sel:DWORD dst_unused:UNUSED_PAD src0_sel:WORD_1 src1_sel:DWORD
	v_or_b32_sdwa v140, v140, v136 dst_sel:DWORD dst_unused:UNUSED_PAD src0_sel:WORD_1 src1_sel:DWORD
	v_mov_b32_e32 v137, v94
	v_mov_b32_e32 v94, v93
	v_mov_b32_e32 v136, v92
	v_pk_add_f32 v[94:95], v[94:95], v[140:141]
	v_lshlrev_b32_e32 v92, 16, v139
	v_lshlrev_b32_e32 v140, 16, v138
	v_and_b32_e32 v139, 0xffff0000, v139
	v_and_b32_e32 v138, 0xffff0000, v138
	v_or_b32_sdwa v93, v143, v92 dst_sel:DWORD dst_unused:UNUSED_PAD src0_sel:WORD_0 src1_sel:DWORD
	v_or_b32_sdwa v92, v142, v140 dst_sel:DWORD dst_unused:UNUSED_PAD src0_sel:WORD_0 src1_sel:DWORD
	v_or_b32_sdwa v139, v143, v139 dst_sel:DWORD dst_unused:UNUSED_PAD src0_sel:WORD_1 src1_sel:DWORD
	v_or_b32_sdwa v138, v142, v138 dst_sel:DWORD dst_unused:UNUSED_PAD src0_sel:WORD_1 src1_sel:DWORD
	v_mov_b32_e32 v140, v88
	v_mov_b32_e32 v141, v90
	v_mov_b32_e32 v90, v89
	v_pk_add_f32 v[136:137], v[136:137], v[152:153]
	v_pk_add_f32 v[92:93], v[140:141], v[92:93]
	v_pk_add_f32 v[90:91], v[90:91], v[138:139]
	v_lshl_add_u64 v[88:89], v[200:201], 2, s[2:3]
	s_cbranch_vccnz .LBB0_1015
	v_mov_b32_e32 v138, v136
	v_mov_b32_e32 v139, v94
	v_mov_b32_e32 v140, v137
	v_mov_b32_e32 v141, v95
	global_store_dwordx4 v[88:89], v[138:141], off
	s_mov_b64 s[34:35], 0
	s_nop 0
	v_mov_b32_e32 v138, v92
	v_mov_b32_e32 v139, v90
	v_mov_b32_e32 v140, v93
	v_mov_b32_e32 v141, v91
	global_store_dwordx4 v[88:89], v[138:141], off offset:16
	s_branch .LBB0_1016

.LBB0_1016:
	s_nop 0
	v_and_b32_e32 v141, 0xffff0000, v94
	v_and_b32_e32 v140, 0xffff0000, v95
	v_and_b32_e32 v138, 0xffff0000, v90
	s_andn2_b64 vcc, exec, s[34:35]
	v_and_b32_e32 v139, 0xffff0000, v91
	s_cbranch_vccnz .LBB0_1018
	v_or_b32_sdwa v152, v136, v141 dst_sel:DWORD dst_unused:UNUSED_PAD src0_sel:WORD_1 src1_sel:DWORD
	v_or_b32_sdwa v153, v137, v140 dst_sel:DWORD dst_unused:UNUSED_PAD src0_sel:WORD_1 src1_sel:DWORD
	v_or_b32_sdwa v154, v92, v138 dst_sel:DWORD dst_unused:UNUSED_PAD src0_sel:WORD_1 src1_sel:DWORD
	v_or_b32_sdwa v155, v93, v139 dst_sel:DWORD dst_unused:UNUSED_PAD src0_sel:WORD_1 src1_sel:DWORD
	v_lshlrev_b32_e32 v94, 16, v94
	v_lshlrev_b32_e32 v95, 16, v95
	v_lshlrev_b32_e32 v90, 16, v90
	v_lshlrev_b32_e32 v91, 16, v91
	s_mov_b32 s4, 0xffff
	v_and_or_b32 v159, v93, s4, v91
	v_and_or_b32 v158, v92, s4, v90
	v_and_or_b32 v157, v137, s4, v95
	v_and_or_b32 v156, v136, s4, v94
	global_store_dwordx4 v[196:197], v[152:155], off
	global_store_dwordx4 v[198:199], v[156:159], off nt

.LBB0_1021:
	v_and_b32_e32 v89, 0xffff0000, v86
	v_and_b32_e32 v88, 0xffff0000, v87
	v_and_b32_e32 v82, 0xffff0000, v80
	s_andn2_b64 vcc, exec, s[34:35]
	v_and_b32_e32 v83, 0xffff0000, v81
	s_cbranch_vccnz .LBB0_1023
	v_or_b32_sdwa v128, v90, v89 dst_sel:DWORD dst_unused:UNUSED_PAD src0_sel:WORD_1 src1_sel:DWORD
	v_or_b32_sdwa v129, v91, v88 dst_sel:DWORD dst_unused:UNUSED_PAD src0_sel:WORD_1 src1_sel:DWORD
	v_or_b32_sdwa v130, v84, v82 dst_sel:DWORD dst_unused:UNUSED_PAD src0_sel:WORD_1 src1_sel:DWORD
	v_or_b32_sdwa v131, v85, v83 dst_sel:DWORD dst_unused:UNUSED_PAD src0_sel:WORD_1 src1_sel:DWORD
	v_lshlrev_b32_e32 v86, 16, v86
	v_lshlrev_b32_e32 v87, 16, v87
	v_lshlrev_b32_e32 v80, 16, v80
	v_lshlrev_b32_e32 v81, 16, v81
	s_mov_b32 s4, 0xffff
	v_and_or_b32 v135, v85, s4, v81
	v_and_or_b32 v134, v84, s4, v80
	v_and_or_b32 v133, v91, s4, v87
	v_and_or_b32 v132, v90, s4, v86
	global_store_dwordx4 v[196:197], v[128:131], off offset:256
	global_store_dwordx4 v[198:199], v[132:135], off offset:256 nt

.LBB0_1025:
	s_or_b64 exec, exec, s[34:35]
	v_add_u32_e32 v128, 0x90, v192
	v_ashrrev_i32_e32 v129, 31, v128
	s_waitcnt lgkmcnt(0)
	v_lshlrev_b64 v[80:81], 10, v[128:129]
	v_lshl_add_u64 v[134:135], v[80:81], 0, v[190:191]
	v_readlane_b32 s34, v247, 5
	v_lshlrev_b64 v[80:81], 1, v[134:135]
	v_readlane_b32 s35, v247, 6
	s_and_b64 vcc, exec, s[8:9]
	s_nop 0
	v_lshl_add_u64 v[130:131], s[34:35], 0, v[80:81]
	v_readlane_b32 s34, v249, 0
	v_readlane_b32 s35, v249, 1
	global_load_dwordx4 v[88:91], v[130:131], off offset:0
	s_nop 1
	v_lshl_add_u64 v[132:133], s[34:35], 0, v[80:81]
	global_load_dwordx4 v[92:95], v[132:133], off offset:0 nt
	global_load_dwordx4 v[84:87], v[130:131], off offset:256
	global_load_dwordx4 v[80:83], v[132:133], off offset:256 nt
	s_waitcnt vmcnt(8)
	s_nop 0
	v_lshlrev_b32_e32 v136, 16, v121
	v_lshlrev_b32_e32 v138, 16, v120
	v_and_b32_e32 v121, 0xffff0000, v121
	v_and_b32_e32 v120, 0xffff0000, v120
	v_or_b32_sdwa v137, v125, v136 dst_sel:DWORD dst_unused:UNUSED_PAD src0_sel:WORD_0 src1_sel:DWORD
	v_or_b32_sdwa v136, v124, v138 dst_sel:DWORD dst_unused:UNUSED_PAD src0_sel:WORD_0 src1_sel:DWORD
	v_or_b32_sdwa v125, v125, v121 dst_sel:DWORD dst_unused:UNUSED_PAD src0_sel:WORD_1 src1_sel:DWORD
	v_or_b32_sdwa v124, v124, v120 dst_sel:DWORD dst_unused:UNUSED_PAD src0_sel:WORD_1 src1_sel:DWORD
	v_mov_b32_e32 v121, v78
	v_mov_b32_e32 v78, v77
	v_mov_b32_e32 v120, v76
	v_pk_add_f32 v[78:79], v[78:79], v[124:125]
	v_lshlrev_b32_e32 v76, 16, v123
	v_lshlrev_b32_e32 v124, 16, v122
	v_and_b32_e32 v123, 0xffff0000, v123
	v_and_b32_e32 v122, 0xffff0000, v122
	v_or_b32_sdwa v77, v127, v76 dst_sel:DWORD dst_unused:UNUSED_PAD src0_sel:WORD_0 src1_sel:DWORD
	v_or_b32_sdwa v76, v126, v124 dst_sel:DWORD dst_unused:UNUSED_PAD src0_sel:WORD_0 src1_sel:DWORD
	v_or_b32_sdwa v123, v127, v123 dst_sel:DWORD dst_unused:UNUSED_PAD src0_sel:WORD_1 src1_sel:DWORD
	v_or_b32_sdwa v122, v126, v122 dst_sel:DWORD dst_unused:UNUSED_PAD src0_sel:WORD_1 src1_sel:DWORD
	v_mov_b32_e32 v124, v72
	v_mov_b32_e32 v125, v74
	v_mov_b32_e32 v74, v73
	v_pk_add_f32 v[120:121], v[120:121], v[136:137]
	v_pk_add_f32 v[76:77], v[124:125], v[76:77]
	v_pk_add_f32 v[74:75], v[74:75], v[122:123]
	v_lshl_add_u64 v[72:73], v[166:167], 2, s[2:3]
	s_cbranch_vccnz .LBB0_1027
	v_mov_b32_e32 v122, v120
	v_mov_b32_e32 v123, v78
	v_mov_b32_e32 v124, v121
	v_mov_b32_e32 v125, v79
	global_store_dwordx4 v[72:73], v[122:125], off
	s_mov_b64 s[34:35], 0
	s_nop 0
	v_mov_b32_e32 v122, v76
	v_mov_b32_e32 v123, v74
	v_mov_b32_e32 v124, v77
	v_mov_b32_e32 v125, v75
	global_store_dwordx4 v[72:73], v[122:125], off offset:16
	s_branch .LBB0_1028

.LBB0_1028:
	s_nop 0
	v_and_b32_e32 v125, 0xffff0000, v78
	v_and_b32_e32 v124, 0xffff0000, v79
	v_and_b32_e32 v122, 0xffff0000, v74
	s_andn2_b64 vcc, exec, s[34:35]
	v_and_b32_e32 v123, 0xffff0000, v75
	s_cbranch_vccnz .LBB0_1030
	v_or_b32_sdwa v136, v120, v125 dst_sel:DWORD dst_unused:UNUSED_PAD src0_sel:WORD_1 src1_sel:DWORD
	v_or_b32_sdwa v137, v121, v124 dst_sel:DWORD dst_unused:UNUSED_PAD src0_sel:WORD_1 src1_sel:DWORD
	v_or_b32_sdwa v138, v76, v122 dst_sel:DWORD dst_unused:UNUSED_PAD src0_sel:WORD_1 src1_sel:DWORD
	v_or_b32_sdwa v139, v77, v123 dst_sel:DWORD dst_unused:UNUSED_PAD src0_sel:WORD_1 src1_sel:DWORD
	v_lshlrev_b32_e32 v78, 16, v78
	v_lshlrev_b32_e32 v79, 16, v79
	v_lshlrev_b32_e32 v74, 16, v74
	v_lshlrev_b32_e32 v75, 16, v75
	s_mov_b32 s4, 0xffff
	v_and_or_b32 v143, v77, s4, v75
	v_and_or_b32 v142, v76, s4, v74
	v_and_or_b32 v141, v121, s4, v79
	v_and_or_b32 v140, v120, s4, v78
	global_store_dwordx4 v[162:163], v[136:139], off
	global_store_dwordx4 v[164:165], v[140:143], off nt

.LBB0_1033:
	v_and_b32_e32 v73, 0xffff0000, v70
	v_and_b32_e32 v72, 0xffff0000, v71
	v_and_b32_e32 v66, 0xffff0000, v64
	s_andn2_b64 vcc, exec, s[34:35]
	v_and_b32_e32 v67, 0xffff0000, v65
	s_cbranch_vccnz .LBB0_1035
	v_or_b32_sdwa v112, v74, v73 dst_sel:DWORD dst_unused:UNUSED_PAD src0_sel:WORD_1 src1_sel:DWORD
	v_or_b32_sdwa v113, v75, v72 dst_sel:DWORD dst_unused:UNUSED_PAD src0_sel:WORD_1 src1_sel:DWORD
	v_or_b32_sdwa v114, v68, v66 dst_sel:DWORD dst_unused:UNUSED_PAD src0_sel:WORD_1 src1_sel:DWORD
	v_or_b32_sdwa v115, v69, v67 dst_sel:DWORD dst_unused:UNUSED_PAD src0_sel:WORD_1 src1_sel:DWORD
	v_lshlrev_b32_e32 v70, 16, v70
	v_lshlrev_b32_e32 v71, 16, v71
	v_lshlrev_b32_e32 v64, 16, v64
	v_lshlrev_b32_e32 v65, 16, v65
	s_mov_b32 s4, 0xffff
	v_and_or_b32 v119, v69, s4, v65
	v_and_or_b32 v118, v68, s4, v64
	v_and_or_b32 v117, v75, s4, v71
	v_and_or_b32 v116, v74, s4, v70
	global_store_dwordx4 v[162:163], v[112:115], off offset:256
	global_store_dwordx4 v[164:165], v[116:119], off offset:256 nt

.LBB0_1037:
	s_or_b64 exec, exec, s[34:35]
	v_add_u32_e32 v112, 0xa0, v192
	v_ashrrev_i32_e32 v113, 31, v112
	s_waitcnt lgkmcnt(0)
	v_lshlrev_b64 v[64:65], 10, v[112:113]
	v_lshl_add_u64 v[118:119], v[64:65], 0, v[190:191]
	v_readlane_b32 s34, v247, 5
	v_lshlrev_b64 v[64:65], 1, v[118:119]
	v_readlane_b32 s35, v247, 6
	s_and_b64 vcc, exec, s[8:9]
	s_nop 0
	v_lshl_add_u64 v[114:115], s[34:35], 0, v[64:65]
	v_readlane_b32 s34, v249, 0
	v_readlane_b32 s35, v249, 1
	global_load_dwordx4 v[72:75], v[114:115], off offset:0
	s_nop 1
	v_lshl_add_u64 v[116:117], s[34:35], 0, v[64:65]
	global_load_dwordx4 v[76:79], v[116:117], off offset:0 nt
	global_load_dwordx4 v[68:71], v[114:115], off offset:256
	global_load_dwordx4 v[64:67], v[116:117], off offset:256 nt
	s_waitcnt vmcnt(8)
	s_nop 0
	v_lshlrev_b32_e32 v120, 16, v105
	v_lshlrev_b32_e32 v122, 16, v104
	v_and_b32_e32 v105, 0xffff0000, v105
	v_and_b32_e32 v104, 0xffff0000, v104
	v_or_b32_sdwa v121, v109, v120 dst_sel:DWORD dst_unused:UNUSED_PAD src0_sel:WORD_0 src1_sel:DWORD
	v_or_b32_sdwa v120, v108, v122 dst_sel:DWORD dst_unused:UNUSED_PAD src0_sel:WORD_0 src1_sel:DWORD
	v_or_b32_sdwa v109, v109, v105 dst_sel:DWORD dst_unused:UNUSED_PAD src0_sel:WORD_1 src1_sel:DWORD
	v_or_b32_sdwa v108, v108, v104 dst_sel:DWORD dst_unused:UNUSED_PAD src0_sel:WORD_1 src1_sel:DWORD
	v_mov_b32_e32 v105, v62
	v_mov_b32_e32 v62, v61
	v_mov_b32_e32 v104, v60
	v_pk_add_f32 v[62:63], v[62:63], v[108:109]
	v_lshlrev_b32_e32 v60, 16, v107
	v_lshlrev_b32_e32 v108, 16, v106
	v_and_b32_e32 v107, 0xffff0000, v107
	v_and_b32_e32 v106, 0xffff0000, v106
	v_or_b32_sdwa v61, v111, v60 dst_sel:DWORD dst_unused:UNUSED_PAD src0_sel:WORD_0 src1_sel:DWORD
	v_or_b32_sdwa v60, v110, v108 dst_sel:DWORD dst_unused:UNUSED_PAD src0_sel:WORD_0 src1_sel:DWORD
	v_or_b32_sdwa v107, v111, v107 dst_sel:DWORD dst_unused:UNUSED_PAD src0_sel:WORD_1 src1_sel:DWORD
	v_or_b32_sdwa v106, v110, v106 dst_sel:DWORD dst_unused:UNUSED_PAD src0_sel:WORD_1 src1_sel:DWORD
	v_mov_b32_e32 v108, v56
	v_mov_b32_e32 v109, v58
	v_mov_b32_e32 v58, v57
	v_pk_add_f32 v[104:105], v[104:105], v[120:121]
	v_pk_add_f32 v[60:61], v[108:109], v[60:61]
	v_pk_add_f32 v[58:59], v[58:59], v[106:107]
	v_lshl_add_u64 v[56:57], v[150:151], 2, s[2:3]
	s_cbranch_vccnz .LBB0_1039
	v_mov_b32_e32 v106, v104
	v_mov_b32_e32 v107, v62
	v_mov_b32_e32 v108, v105
	v_mov_b32_e32 v109, v63
	global_store_dwordx4 v[56:57], v[106:109], off
	s_mov_b64 s[34:35], 0
	s_nop 0
	v_mov_b32_e32 v106, v60
	v_mov_b32_e32 v107, v58
	v_mov_b32_e32 v108, v61
	v_mov_b32_e32 v109, v59
	global_store_dwordx4 v[56:57], v[106:109], off offset:16
	s_branch .LBB0_1040

.LBB0_1040:
	s_nop 0
	v_and_b32_e32 v109, 0xffff0000, v62
	v_and_b32_e32 v108, 0xffff0000, v63
	v_and_b32_e32 v106, 0xffff0000, v58
	s_andn2_b64 vcc, exec, s[34:35]
	v_and_b32_e32 v107, 0xffff0000, v59
	s_cbranch_vccnz .LBB0_1042
	v_or_b32_sdwa v120, v109, v104 dst_sel:DWORD dst_unused:UNUSED_PAD src0_sel:DWORD src1_sel:WORD_1
	v_or_b32_sdwa v121, v108, v105 dst_sel:DWORD dst_unused:UNUSED_PAD src0_sel:DWORD src1_sel:WORD_1
	v_or_b32_sdwa v122, v106, v60 dst_sel:DWORD dst_unused:UNUSED_PAD src0_sel:DWORD src1_sel:WORD_1
	v_or_b32_sdwa v123, v107, v61 dst_sel:DWORD dst_unused:UNUSED_PAD src0_sel:DWORD src1_sel:WORD_1
	v_and_b32_e32 v110, 0xffff, v104
	v_and_b32_e32 v111, 0xffff, v105
	v_and_b32_e32 v124, 0xffff, v60
	v_and_b32_e32 v125, 0xffff, v61
	v_lshl_or_b32 v127, v59, 16, v125
	v_lshl_or_b32 v126, v58, 16, v124
	v_lshl_or_b32 v125, v63, 16, v111
	v_lshl_or_b32 v124, v62, 16, v110
	global_store_dwordx4 v[146:147], v[120:123], off
	global_store_dwordx4 v[148:149], v[124:127], off nt

.LBB0_1045:
	v_and_b32_e32 v57, 0xffff0000, v54
	v_and_b32_e32 v56, 0xffff0000, v55
	v_and_b32_e32 v50, 0xffff0000, v48
	s_andn2_b64 vcc, exec, s[34:35]
	v_and_b32_e32 v51, 0xffff0000, v49
	s_cbranch_vccnz .LBB0_1047
	v_or_b32_sdwa v96, v57, v58 dst_sel:DWORD dst_unused:UNUSED_PAD src0_sel:DWORD src1_sel:WORD_1
	v_or_b32_sdwa v97, v56, v59 dst_sel:DWORD dst_unused:UNUSED_PAD src0_sel:DWORD src1_sel:WORD_1
	v_or_b32_sdwa v98, v50, v52 dst_sel:DWORD dst_unused:UNUSED_PAD src0_sel:DWORD src1_sel:WORD_1
	v_or_b32_sdwa v99, v51, v53 dst_sel:DWORD dst_unused:UNUSED_PAD src0_sel:DWORD src1_sel:WORD_1
	v_and_b32_e32 v62, 0xffff, v58
	v_and_b32_e32 v63, 0xffff, v59
	v_and_b32_e32 v100, 0xffff, v52
	v_and_b32_e32 v101, 0xffff, v53
	v_lshl_or_b32 v103, v49, 16, v101
	v_lshl_or_b32 v102, v48, 16, v100
	v_lshl_or_b32 v101, v55, 16, v63
	v_lshl_or_b32 v100, v54, 16, v62
	global_store_dwordx4 v[146:147], v[96:99], off offset:256
	global_store_dwordx4 v[148:149], v[100:103], off offset:256 nt

.LBB0_1049:
	s_or_b64 exec, exec, s[34:35]
	v_add_u32_e32 v96, 0xb0, v192
	v_ashrrev_i32_e32 v97, 31, v96
	s_waitcnt lgkmcnt(0)
	v_lshlrev_b64 v[48:49], 10, v[96:97]
	v_lshl_add_u64 v[102:103], v[48:49], 0, v[190:191]
	v_readlane_b32 s34, v247, 5
	v_lshlrev_b64 v[48:49], 1, v[102:103]
	v_readlane_b32 s35, v247, 6
	s_and_b64 vcc, exec, s[8:9]
	s_nop 0
	v_lshl_add_u64 v[98:99], s[34:35], 0, v[48:49]
	v_readlane_b32 s34, v249, 0
	v_readlane_b32 s35, v249, 1
	global_load_dwordx4 v[56:59], v[98:99], off offset:0
	s_nop 1
	v_lshl_add_u64 v[100:101], s[34:35], 0, v[48:49]
	global_load_dwordx4 v[60:63], v[100:101], off offset:0 nt
	global_load_dwordx4 v[52:55], v[98:99], off offset:256
	global_load_dwordx4 v[48:51], v[100:101], off offset:256 nt
	s_waitcnt vmcnt(8)
	s_nop 0
	v_lshlrev_b32_e32 v104, 16, v89
	v_lshlrev_b32_e32 v106, 16, v88
	v_and_b32_e32 v89, 0xffff0000, v89
	v_and_b32_e32 v88, 0xffff0000, v88
	v_or_b32_sdwa v105, v93, v104 dst_sel:DWORD dst_unused:UNUSED_PAD src0_sel:WORD_0 src1_sel:DWORD
	v_or_b32_sdwa v104, v92, v106 dst_sel:DWORD dst_unused:UNUSED_PAD src0_sel:WORD_0 src1_sel:DWORD
	v_or_b32_sdwa v93, v93, v89 dst_sel:DWORD dst_unused:UNUSED_PAD src0_sel:WORD_1 src1_sel:DWORD
	v_or_b32_sdwa v92, v92, v88 dst_sel:DWORD dst_unused:UNUSED_PAD src0_sel:WORD_1 src1_sel:DWORD
	v_mov_b32_e32 v89, v46
	v_mov_b32_e32 v46, v45
	v_mov_b32_e32 v88, v44
	v_pk_add_f32 v[46:47], v[46:47], v[92:93]
	v_lshlrev_b32_e32 v44, 16, v91
	v_lshlrev_b32_e32 v92, 16, v90
	v_and_b32_e32 v91, 0xffff0000, v91
	v_and_b32_e32 v90, 0xffff0000, v90
	v_or_b32_sdwa v45, v95, v44 dst_sel:DWORD dst_unused:UNUSED_PAD src0_sel:WORD_0 src1_sel:DWORD
	v_or_b32_sdwa v44, v94, v92 dst_sel:DWORD dst_unused:UNUSED_PAD src0_sel:WORD_0 src1_sel:DWORD
	v_or_b32_sdwa v91, v95, v91 dst_sel:DWORD dst_unused:UNUSED_PAD src0_sel:WORD_1 src1_sel:DWORD
	v_or_b32_sdwa v90, v94, v90 dst_sel:DWORD dst_unused:UNUSED_PAD src0_sel:WORD_1 src1_sel:DWORD
	v_mov_b32_e32 v92, v40
	v_mov_b32_e32 v93, v42
	v_mov_b32_e32 v42, v41
	v_pk_add_f32 v[88:89], v[88:89], v[104:105]
	v_pk_add_f32 v[44:45], v[92:93], v[44:45]
	v_pk_add_f32 v[42:43], v[42:43], v[90:91]
	v_lshl_add_u64 v[40:41], v[134:135], 2, s[2:3]
	s_cbranch_vccnz .LBB0_1051
	v_mov_b32_e32 v90, v88
	v_mov_b32_e32 v91, v46
	v_mov_b32_e32 v92, v89
	v_mov_b32_e32 v93, v47
	global_store_dwordx4 v[40:41], v[90:93], off
	s_mov_b64 s[34:35], 0
	s_nop 0
	v_mov_b32_e32 v90, v44
	v_mov_b32_e32 v91, v42
	v_mov_b32_e32 v92, v45
	v_mov_b32_e32 v93, v43
	global_store_dwordx4 v[40:41], v[90:93], off offset:16
	s_branch .LBB0_1052

.LBB0_1052:
	s_nop 0
	v_and_b32_e32 v93, 0xffff0000, v46
	v_and_b32_e32 v92, 0xffff0000, v47
	v_and_b32_e32 v90, 0xffff0000, v42
	s_andn2_b64 vcc, exec, s[34:35]
	v_and_b32_e32 v91, 0xffff0000, v43
	s_cbranch_vccnz .LBB0_1054
	v_or_b32_sdwa v104, v93, v88 dst_sel:DWORD dst_unused:UNUSED_PAD src0_sel:DWORD src1_sel:WORD_1
	v_or_b32_sdwa v105, v92, v89 dst_sel:DWORD dst_unused:UNUSED_PAD src0_sel:DWORD src1_sel:WORD_1
	v_or_b32_sdwa v106, v90, v44 dst_sel:DWORD dst_unused:UNUSED_PAD src0_sel:DWORD src1_sel:WORD_1
	v_or_b32_sdwa v107, v91, v45 dst_sel:DWORD dst_unused:UNUSED_PAD src0_sel:DWORD src1_sel:WORD_1
	v_and_b32_e32 v94, 0xffff, v88
	v_and_b32_e32 v95, 0xffff, v89
	v_and_b32_e32 v108, 0xffff, v44
	v_and_b32_e32 v109, 0xffff, v45
	v_lshl_or_b32 v111, v43, 16, v109
	v_lshl_or_b32 v110, v42, 16, v108
	v_lshl_or_b32 v109, v47, 16, v95
	v_lshl_or_b32 v108, v46, 16, v94
	global_store_dwordx4 v[130:131], v[104:107], off
	global_store_dwordx4 v[132:133], v[108:111], off nt

.LBB0_1057:
	v_and_b32_e32 v41, 0xffff0000, v38
	v_and_b32_e32 v40, 0xffff0000, v39
	v_and_b32_e32 v34, 0xffff0000, v32
	s_andn2_b64 vcc, exec, s[34:35]
	v_and_b32_e32 v35, 0xffff0000, v33
	s_cbranch_vccnz .LBB0_1059
	v_or_b32_sdwa v80, v41, v42 dst_sel:DWORD dst_unused:UNUSED_PAD src0_sel:DWORD src1_sel:WORD_1
	v_or_b32_sdwa v81, v40, v43 dst_sel:DWORD dst_unused:UNUSED_PAD src0_sel:DWORD src1_sel:WORD_1
	v_or_b32_sdwa v82, v34, v36 dst_sel:DWORD dst_unused:UNUSED_PAD src0_sel:DWORD src1_sel:WORD_1
	v_or_b32_sdwa v83, v35, v37 dst_sel:DWORD dst_unused:UNUSED_PAD src0_sel:DWORD src1_sel:WORD_1
	v_and_b32_e32 v46, 0xffff, v42
	v_and_b32_e32 v47, 0xffff, v43
	v_and_b32_e32 v84, 0xffff, v36
	v_and_b32_e32 v85, 0xffff, v37
	v_lshl_or_b32 v87, v33, 16, v85
	v_lshl_or_b32 v86, v32, 16, v84
	v_lshl_or_b32 v85, v39, 16, v47
	v_lshl_or_b32 v84, v38, 16, v46
	global_store_dwordx4 v[130:131], v[80:83], off offset:256
	global_store_dwordx4 v[132:133], v[84:87], off offset:256 nt

.LBB0_1064:
	s_nop 0
	v_and_b32_e32 v37, 0xffff0000, v30
	v_and_b32_e32 v36, 0xffff0000, v31
	v_and_b32_e32 v34, 0xffff0000, v26
	s_andn2_b64 vcc, exec, s[34:35]
	v_and_b32_e32 v35, 0xffff0000, v27
	s_cbranch_vccnz .LBB0_1066
	v_or_b32_sdwa v38, v37, v32 dst_sel:DWORD dst_unused:UNUSED_PAD src0_sel:DWORD src1_sel:WORD_1
	v_or_b32_sdwa v39, v36, v33 dst_sel:DWORD dst_unused:UNUSED_PAD src0_sel:DWORD src1_sel:WORD_1
	v_or_b32_sdwa v40, v34, v28 dst_sel:DWORD dst_unused:UNUSED_PAD src0_sel:DWORD src1_sel:WORD_1
	v_or_b32_sdwa v41, v35, v29 dst_sel:DWORD dst_unused:UNUSED_PAD src0_sel:DWORD src1_sel:WORD_1
	v_and_b32_e32 v42, 0xffff, v32
	v_and_b32_e32 v43, 0xffff, v33
	v_and_b32_e32 v44, 0xffff, v28
	v_and_b32_e32 v45, 0xffff, v29
	v_lshl_or_b32 v45, v27, 16, v45
	v_lshl_or_b32 v44, v26, 16, v44
	v_lshl_or_b32 v43, v31, 16, v43
	v_lshl_or_b32 v42, v30, 16, v42
	global_store_dwordx4 v[114:115], v[38:41], off
	global_store_dwordx4 v[116:117], v[42:45], off nt

.LBB0_1069:
	v_and_b32_e32 v25, 0xffff0000, v22
	v_and_b32_e32 v24, 0xffff0000, v23
	v_and_b32_e32 v18, 0xffff0000, v16
	s_andn2_b64 vcc, exec, s[34:35]
	v_and_b32_e32 v19, 0xffff0000, v17
	s_cbranch_vccnz .LBB0_1071
	v_or_b32_sdwa v38, v25, v26 dst_sel:DWORD dst_unused:UNUSED_PAD src0_sel:DWORD src1_sel:WORD_1
	v_or_b32_sdwa v39, v24, v27 dst_sel:DWORD dst_unused:UNUSED_PAD src0_sel:DWORD src1_sel:WORD_1
	v_or_b32_sdwa v40, v18, v20 dst_sel:DWORD dst_unused:UNUSED_PAD src0_sel:DWORD src1_sel:WORD_1
	v_or_b32_sdwa v41, v19, v21 dst_sel:DWORD dst_unused:UNUSED_PAD src0_sel:DWORD src1_sel:WORD_1
	v_and_b32_e32 v30, 0xffff, v26
	v_and_b32_e32 v31, 0xffff, v27
	v_and_b32_e32 v42, 0xffff, v20
	v_and_b32_e32 v43, 0xffff, v21
	v_lshl_or_b32 v45, v17, 16, v43
	v_lshl_or_b32 v44, v16, 16, v42
	v_lshl_or_b32 v43, v23, 16, v31
	v_lshl_or_b32 v42, v22, 16, v30
	global_store_dwordx4 v[114:115], v[38:41], off offset:256
	global_store_dwordx4 v[116:117], v[42:45], off offset:256 nt

.LBB0_1076:
	s_nop 0
	v_and_b32_e32 v21, 0xffff0000, v14
	v_and_b32_e32 v20, 0xffff0000, v15
	v_and_b32_e32 v18, 0xffff0000, v10
	s_andn2_b64 vcc, exec, s[34:35]
	v_and_b32_e32 v19, 0xffff0000, v11
	s_cbranch_vccnz .LBB0_1078
	v_or_b32_sdwa v22, v21, v16 dst_sel:DWORD dst_unused:UNUSED_PAD src0_sel:DWORD src1_sel:WORD_1
	v_or_b32_sdwa v23, v20, v17 dst_sel:DWORD dst_unused:UNUSED_PAD src0_sel:DWORD src1_sel:WORD_1
	v_or_b32_sdwa v24, v18, v12 dst_sel:DWORD dst_unused:UNUSED_PAD src0_sel:DWORD src1_sel:WORD_1
	v_or_b32_sdwa v25, v19, v13 dst_sel:DWORD dst_unused:UNUSED_PAD src0_sel:DWORD src1_sel:WORD_1
	v_and_b32_e32 v26, 0xffff, v16
	v_and_b32_e32 v27, 0xffff, v17
	v_and_b32_e32 v28, 0xffff, v12
	v_and_b32_e32 v29, 0xffff, v13
	v_lshl_or_b32 v29, v11, 16, v29
	v_lshl_or_b32 v28, v10, 16, v28
	v_lshl_or_b32 v27, v15, 16, v27
	v_lshl_or_b32 v26, v14, 16, v26
	global_store_dwordx4 v[98:99], v[22:25], off
	global_store_dwordx4 v[100:101], v[26:29], off nt

.LBB0_1081:
	v_and_b32_e32 v9, 0xffff0000, v6
	v_and_b32_e32 v8, 0xffff0000, v7
	v_and_b32_e32 v2, 0xffff0000, v0
	s_andn2_b64 vcc, exec, s[8:9]
	v_and_b32_e32 v3, 0xffff0000, v1
	s_cbranch_vccnz .LBB0_1083
	v_or_b32_sdwa v22, v9, v10 dst_sel:DWORD dst_unused:UNUSED_PAD src0_sel:DWORD src1_sel:WORD_1
	v_or_b32_sdwa v23, v8, v11 dst_sel:DWORD dst_unused:UNUSED_PAD src0_sel:DWORD src1_sel:WORD_1
	v_or_b32_sdwa v24, v2, v4 dst_sel:DWORD dst_unused:UNUSED_PAD src0_sel:DWORD src1_sel:WORD_1
	v_or_b32_sdwa v25, v3, v5 dst_sel:DWORD dst_unused:UNUSED_PAD src0_sel:DWORD src1_sel:WORD_1
	v_and_b32_e32 v14, 0xffff, v10
	v_and_b32_e32 v15, 0xffff, v11
	v_and_b32_e32 v26, 0xffff, v4
	v_and_b32_e32 v27, 0xffff, v5
	v_lshl_or_b32 v29, v1, 16, v27
	v_lshl_or_b32 v28, v0, 16, v26
	v_lshl_or_b32 v27, v7, 16, v15
	v_lshl_or_b32 v26, v6, 16, v14
	global_store_dwordx4 v[98:99], v[22:25], off offset:256
	global_store_dwordx4 v[100:101], v[26:29], off offset:256 nt
